# residual GEMMs (out-proj, FFN-down): first K-iteration peeled, C=0 instead of zeroing, first two vmcnt waits relaxed so epilogue stores/atomics drain under MFMAs
# speedup vs baseline: 1.0230x; 1.0042x over previous
; #define PG8_STAGE(bufoff, gbase, voff) do { _Pragma("unroll") for (int _i = 0; _i < 2; ++_i) \
;         __builtin_amdgcn_global_load_lds((const unsigned*)((const char*)(gbase) + (voff)[_i]), (PG8_LAS unsigned*)(lds + (bufoff) + ldsw + _i * 8192), 16, 0, 0); } while (0)
; #define PG8_LDA(dst, b, h) do { _Pragma("unroll") for (int m = 0; m < 4; ++m) _Pragma("unroll") for (int k = 0; k < 2; ++k) dst[m][k] = *(const PG8_LAS bf16x8*)(lds + PG8_SA(b, h) + aoff + m * 2048 + k * 1024); } while (0)
; #define PG8_LDB(dst, b, h) do { _Pragma("unroll") for (int n = 0; n < 2; ++n) _Pragma("unroll") for (int k = 0; k < 2; ++k) dst[n][k] = *(const PG8_LAS bf16x8*)(lds + PG8_SB(b, h) + boff + n * 2048 + k * 1024); } while (0)
; #define PG8_WAIT_V(n) asm volatile("s_waitcnt vmcnt(" #n ")" ::: "memory")
; #define PG8_WAIT_L(n) asm volatile("s_waitcnt lgkmcnt(" #n ")" ::: "memory")
; #define PG8_BAR __builtin_amdgcn_s_barrier()
;     __host__ __device__ __forceinline__ bool next(int i, Unit& u) const { const long L = (long)i * G + c; if (L >= nwg) return false; map((int)L, u); return true; }
; template <class Epi, class Sched, bool ALIGN_EPI = false, bool SP2 = false>
; __device__ __forceinline__ void gemm_phase(PG8_LAS unsigned char* lds, const Gemm g, const Sched& S, const Epi& E) {
;     ...
;         const char* nA = has_next ? (const char*)g.A + (size_t)nxt.pm * tstepA + (size_t)(nxt.k0 >> 6) * kstepA + (nxt.qa > 0 ? hstepA : (size_t)0) : cA; const char* nB = has_next ? (const char*)g.Bt + (size_t)nxt.pn * tstepB + (size_t)nxt.k0 * 2 + (nxt.qb > 0 ? hstepB : (size_t)0) : cB;
;         const bool whole = cur.qa < 0;
;         const int nt = cur.nt;
;         for (int t = 0; t < nt; t += 2) {
;             const bool last = (t == nt - 2);
;             const char* a1 = cA + (size_t)(t + 1) * kstepA;
;             const char* a2 = last ? nA : cA + (size_t)(t + 2) * kstepA; const char* b2 = last ? nB : cB + (size_t)(t + 2) * kstep;
;             const char* a3 = a2 + kstepA; const char* b3 = b2 + kstep;
;             if (last && has_next) S.a_ready(nxt);
;             if constexpr (SP2) {
;             PG8_LDB(B0, 0, 0); PG8_LDB(B1, 0, 1); PG8_SCHED; PG8_LDA(At, 0, 0); PG8_STAGE(PG8_SA(1, 1), a1 + hstepA, voffA);
;             PG8_WAIT_V(8); PG8_WAIT_L(0); PG8_BAR; PG8_MMA(0, 0, At, B0); if (whole) PG8_MMA(0, 1, At, B1); PG8_BAR; PG8_SCHED;
.LBB0_382:
	s_add_i32 s7, s13, s6
	s_ashr_i32 s6, s7, 31
	s_lshr_b32 s6, s6, 28
	s_add_i32 s13, s7, s6
	s_ashr_i32 s6, s13, 4
	s_lshl_b32 s14, s6, 2
	s_sub_i32 s6, 64, s14
	s_min_i32 s15, s6, 4
	s_abs_i32 s16, s15
	v_cvt_f32_u32_e32 v0, s16
	s_sub_i32 s20, 0, s16
	s_and_b32 s13, s13, -16
	s_sub_i32 s7, s7, s13
	v_rcp_iflag_f32_e32 v0, v0
	s_abs_i32 s13, s7
	s_max_i32 s17, s12, 0x100
	s_xor_b32 s19, s7, s15
	v_mul_f32_e32 v0, 0x4f7ffffe, v0
	v_cvt_u32_f32_e32 v0, v0
	s_add_i32 s18, s17, 0xffffff00
	s_ashr_i32 s19, s19, 31
	s_mov_b32 s6, 0
	v_readfirstlane_b32 s21, v0
	s_mul_i32 s20, s20, s21
	s_mul_hi_u32 s20, s21, s20
	s_add_i32 s21, s21, s20
	s_mul_hi_u32 s20, s13, s21
	s_mul_i32 s21, s20, s16
	s_sub_i32 s13, s13, s21
	s_add_i32 s21, s20, 1
	s_sub_i32 s22, s13, s16
	s_cmp_ge_u32 s13, s16
	s_cselect_b32 s20, s21, s20
	s_cselect_b32 s13, s22, s13
	s_add_i32 s21, s20, 1
	s_cmp_ge_u32 s13, s16
	s_cselect_b32 s13, s21, s20
	s_xor_b32 s13, s13, s19
	s_sub_i32 s13, s13, s19
	s_mul_i32 s15, s13, s15
	s_sub_i32 s7, s7, s15
	s_add_i32 s7, s14, s7
	s_lshr_b32 s14, s18, 4
	s_and_b32 s91, s17, 3
	s_add_i32 s16, s14, 64
	s_and_b64 s[14:15], s[56:57], exec
	s_cselect_b32 s58, s7, s16
	s_bfe_u32 s7, s17, 0x20002
	s_and_b64 s[14:15], s[56:57], exec
	s_cselect_b32 s60, s13, s7
	s_lshl_b32 s7, s91, 9
	s_and_b64 s[14:15], s[56:57], exec
	s_cselect_b32 s7, 0, s7
	s_ashr_i32 s59, s58, 31
	s_lshl_b64 s[14:15], s[58:59], 19
	s_add_u32 s13, s36, s14
	s_addc_u32 s14, s37, s15
	s_add_u32 s62, s13, s7
	s_addc_u32 s63, s14, 0
	s_ashr_i32 s61, s60, 31
	s_lshl_b64 s[14:15], s[60:61], 19
	s_add_u32 s13, s4, s14
	s_addc_u32 s14, s5, s15
	s_add_u32 s64, s13, s7
	s_addc_u32 s65, s14, 0
	s_cmpk_lt_i32 s12, 0x140
	s_cselect_b64 s[76:77], -1, 0
	s_and_b64 s[12:13], s[76:77], exec
	s_cselect_b32 s12, s63, s83
	s_cselect_b32 s13, s62, s82
	s_cselect_b32 s14, s65, s85
	s_cselect_b32 s15, s64, s84
	s_add_i32 s16, s9, -2
	s_add_u32 s82, s82, 0x40080
	s_addc_u32 s83, s83, 0
	s_add_u32 s17, s84, 0x100
	s_addc_u32 s18, s85, 0
	s_waitcnt lgkmcnt(0)
	ds_read_b128 v[128:131], v242
	ds_read_b128 v[132:135], v242 offset:1024
	ds_read_b128 v[136:139], v242 offset:2048
	ds_read_b128 v[140:143], v242 offset:3072
	ds_read_b128 v[144:147], v243
	ds_read_b128 v[148:151], v243 offset:1024
	ds_read_b128 v[152:155], v243 offset:2048
	ds_read_b128 v[156:159], v243 offset:3072
	s_add_i32 s19, s6, 2
	s_add_u32 s7, s82, 0xfffc0080
	s_addc_u32 s20, s83, -1
	s_cmp_eq_u32 s16, s6
	s_cselect_b32 s6, s15, s17
	s_cselect_b32 s85, s12, s20
	s_cselect_b32 s84, s13, s7
	s_cselect_b32 s7, s14, s18
	v_lshl_add_u64 v[204:205], s[82:83], 0, v[200:201]
	s_add_i32 m0, s28, 0xc000
	ds_read_b128 v[160:163], v244
	ds_read_b128 v[164:167], v244 offset:1024
	ds_read_b128 v[168:171], v244 offset:2048
	ds_read_b128 v[172:175], v244 offset:3072
	ds_read_b128 v[176:179], v244 offset:4096
	ds_read_b128 v[180:183], v244 offset:5120
	ds_read_b128 v[184:187], v244 offset:6144
	ds_read_b128 v[188:191], v244 offset:7168
	global_load_lds_dwordx4 v[204:205], off
	v_lshl_add_u64 v[204:205], s[82:83], 0, v[202:203]
	s_add_i32 m0, s28, 0xe000
	s_nop 0
	global_load_lds_dwordx4 v[204:205], off
	s_waitcnt vmcnt(24)
	s_waitcnt lgkmcnt(0)
	s_barrier
	s_setprio 1
	s_waitcnt lgkmcnt(0)
	v_mfma_f32_16x16x32_bf16 v[124:127], v[128:131], v[160:163], 0
	v_mfma_f32_16x16x32_bf16 v[120:123], v[136:139], v[160:163], 0
	v_mfma_f32_16x16x32_bf16 v[116:119], v[128:131], v[168:171], 0
	v_mfma_f32_16x16x32_bf16 v[108:111], v[136:139], v[168:171], 0
	v_mfma_f32_16x16x32_bf16 v[100:103], v[128:131], v[176:179], 0
	v_mfma_f32_16x16x32_bf16 v[92:95], v[136:139], v[176:179], 0
	v_mfma_f32_16x16x32_bf16 v[84:87], v[128:131], v[184:187], 0
	v_mfma_f32_16x16x32_bf16 v[76:79], v[136:139], v[184:187], 0
	v_mfma_f32_16x16x32_bf16 v[124:127], v[132:135], v[164:167], v[124:127]
	v_mfma_f32_16x16x32_bf16 v[120:123], v[140:143], v[164:167], v[120:123]
	v_mfma_f32_16x16x32_bf16 v[116:119], v[132:135], v[172:175], v[116:119]
	v_mfma_f32_16x16x32_bf16 v[108:111], v[140:143], v[172:175], v[108:111]
	v_mfma_f32_16x16x32_bf16 v[100:103], v[132:135], v[180:183], v[100:103]
	v_mfma_f32_16x16x32_bf16 v[92:95], v[140:143], v[180:183], v[92:95]
	v_mfma_f32_16x16x32_bf16 v[84:87], v[132:135], v[188:191], v[84:87]
	v_mfma_f32_16x16x32_bf16 v[76:79], v[140:143], v[188:191], v[76:79]
	s_setprio 0
	s_setprio 1
	v_mfma_f32_16x16x32_bf16 v[112:115], v[144:147], v[160:163], 0
	v_mfma_f32_16x16x32_bf16 v[104:107], v[152:155], v[160:163], 0
	v_mfma_f32_16x16x32_bf16 v[96:99], v[144:147], v[168:171], 0
	v_mfma_f32_16x16x32_bf16 v[88:91], v[152:155], v[168:171], 0
	v_mfma_f32_16x16x32_bf16 v[80:83], v[144:147], v[176:179], 0
	v_mfma_f32_16x16x32_bf16 v[72:75], v[152:155], v[176:179], 0
	v_mfma_f32_16x16x32_bf16 v[68:71], v[144:147], v[184:187], 0
	v_mfma_f32_16x16x32_bf16 v[64:67], v[152:155], v[184:187], 0
	v_mfma_f32_16x16x32_bf16 v[112:115], v[148:151], v[164:167], v[112:115]
	v_mfma_f32_16x16x32_bf16 v[104:107], v[156:159], v[164:167], v[104:107]
	v_mfma_f32_16x16x32_bf16 v[96:99], v[148:151], v[172:175], v[96:99]
	v_mfma_f32_16x16x32_bf16 v[88:91], v[156:159], v[172:175], v[88:91]
	v_mfma_f32_16x16x32_bf16 v[80:83], v[148:151], v[180:183], v[80:83]
	v_mfma_f32_16x16x32_bf16 v[72:75], v[156:159], v[180:183], v[72:75]
	v_mfma_f32_16x16x32_bf16 v[68:71], v[148:151], v[188:191], v[68:71]
	v_mfma_f32_16x16x32_bf16 v[64:67], v[156:159], v[188:191], v[64:67]
	s_setprio 0
	s_barrier
; #define PG8_STAGE(bufoff, gbase, voff) do { _Pragma("unroll") for (int _i = 0; _i < 2; ++_i) \
;         __builtin_amdgcn_global_load_lds((const unsigned*)((const char*)(gbase) + (voff)[_i]), (PG8_LAS unsigned*)(lds + (bufoff) + ldsw + _i * 8192), 16, 0, 0); } while (0)
; #define PG8_LDA(dst, b, h) do { _Pragma("unroll") for (int m = 0; m < 4; ++m) _Pragma("unroll") for (int k = 0; k < 2; ++k) dst[m][k] = *(const PG8_LAS bf16x8*)(lds + PG8_SA(b, h) + aoff + m * 2048 + k * 1024); } while (0)
; #define PG8_LDB(dst, b, h) do { _Pragma("unroll") for (int n = 0; n < 2; ++n) _Pragma("unroll") for (int k = 0; k < 2; ++k) dst[n][k] = *(const PG8_LAS bf16x8*)(lds + PG8_SB(b, h) + boff + n * 2048 + k * 1024); } while (0)
; #define PG8_MMA(ai, bj, At, Bt) do { __builtin_amdgcn_s_setprio(1); _Pragma("unroll") for (int m = 0; m < 4; ++m) _Pragma("unroll") for (int n = 0; n < 2; ++n) _Pragma("unroll") for (int k = 0; k < 2; ++k) \
;         acc[ai][bj][m][n] = __builtin_amdgcn_mfma_f32_16x16x32_bf16(Bt[n][k], At[m][k], acc[ai][bj][m][n], 0, 0, 0); __builtin_amdgcn_s_setprio(0); } while (0)
; #define PG8_WAIT_V(n) asm volatile("s_waitcnt vmcnt(" #n ")" ::: "memory")
; #define PG8_WAIT_L(n) asm volatile("s_waitcnt lgkmcnt(" #n ")" ::: "memory")
; #define PG8_BAR __builtin_amdgcn_s_barrier()
; #define PG8_SCHED __builtin_amdgcn_sched_barrier(0)
; template <class Epi, class Sched, bool ALIGN_EPI = false, bool SP2 = false>
; __device__ __forceinline__ void gemm_phase(PG8_LAS unsigned char* lds, const Gemm g, const Sched& S, const Epi& E) {
;     ...
;             PG8_LDA(At, 0, 1); PG8_STAGE(PG8_SB(0, 0), b2, voffB); PG8_STAGE(PG8_SB(0, 1), b2 + hstepB, voffB); PG8_STAGE(PG8_SA(0, 0), a2, voffA);
;             PG8_WAIT_V(8); PG8_WAIT_L(0); PG8_BAR; if (whole) { PG8_MMA(1, 0, At, B0); PG8_MMA(1, 1, At, B1); } PG8_BAR; PG8_SCHED;
;             PG8_LDB(B0, 1, 0); PG8_LDB(B1, 1, 1); PG8_SCHED; PG8_LDA(At, 1, 0); PG8_STAGE(PG8_SA(0, 1), a2 + hstepA, voffA);
;             PG8_WAIT_V(8); PG8_WAIT_L(0); PG8_BAR; PG8_MMA(0, 0, At, B0); if (whole) PG8_MMA(0, 1, At, B1); PG8_BAR; PG8_SCHED;
	s_add_i32 s20, s86, s8
	v_lshl_add_u64 v[204:205], s[6:7], 0, v[194:195]
	s_mov_b32 m0, s20
	ds_read_b128 v[160:163], v244 offset:16384
	ds_read_b128 v[164:167], v244 offset:17408
	ds_read_b128 v[168:171], v244 offset:18432
	ds_read_b128 v[172:175], v244 offset:19456
	ds_read_b128 v[176:179], v244 offset:20480
	ds_read_b128 v[180:183], v244 offset:21504
	ds_read_b128 v[184:187], v244 offset:22528
	ds_read_b128 v[188:191], v244 offset:23552
	global_load_lds_dwordx4 v[204:205], off
	s_add_i32 m0, s20, 0x2000
	s_add_u32 s20, s6, 0x40000
	v_lshl_add_u64 v[206:207], s[6:7], 0, v[198:199]
	s_addc_u32 s21, s7, 0
	s_add_i32 s22, s87, s8
	global_load_lds_dwordx4 v[206:207], off
	v_lshl_add_u64 v[208:209], s[20:21], 0, v[194:195]
	s_mov_b32 m0, s22
	v_lshl_add_u64 v[210:211], s[84:85], 0, v[196:197]
	global_load_lds_dwordx4 v[208:209], off
	v_lshl_add_u64 v[208:209], s[20:21], 0, v[198:199]
	s_add_i32 m0, s22, 0x2000
	s_nop 0
	global_load_lds_dwordx4 v[208:209], off
	v_lshl_add_u64 v[208:209], s[84:85], 0, v[192:193]
	s_mov_b32 m0, s28
	s_nop 0
	global_load_lds_dwordx4 v[208:209], off
	s_mov_b32 m0, s29
	s_nop 0
	global_load_lds_dwordx4 v[210:211], off
	s_waitcnt vmcnt(24)
	s_waitcnt lgkmcnt(0)
	s_barrier
	s_setprio 1
	s_waitcnt lgkmcnt(0)
	v_mfma_f32_16x16x32_bf16 v[60:63], v[128:131], v[160:163], 0
	v_mfma_f32_16x16x32_bf16 v[56:59], v[136:139], v[160:163], 0
	v_mfma_f32_16x16x32_bf16 v[52:55], v[128:131], v[168:171], 0
	v_mfma_f32_16x16x32_bf16 v[44:47], v[136:139], v[168:171], 0
	v_mfma_f32_16x16x32_bf16 v[36:39], v[128:131], v[176:179], 0
	v_mfma_f32_16x16x32_bf16 v[28:31], v[136:139], v[176:179], 0
	v_mfma_f32_16x16x32_bf16 v[20:23], v[128:131], v[184:187], 0
	v_mfma_f32_16x16x32_bf16 v[12:15], v[136:139], v[184:187], 0
	v_mfma_f32_16x16x32_bf16 v[60:63], v[132:135], v[164:167], v[60:63]
	v_mfma_f32_16x16x32_bf16 v[56:59], v[140:143], v[164:167], v[56:59]
	v_mfma_f32_16x16x32_bf16 v[52:55], v[132:135], v[172:175], v[52:55]
	v_mfma_f32_16x16x32_bf16 v[44:47], v[140:143], v[172:175], v[44:47]
	v_mfma_f32_16x16x32_bf16 v[36:39], v[132:135], v[180:183], v[36:39]
	v_mfma_f32_16x16x32_bf16 v[28:31], v[140:143], v[180:183], v[28:31]
	v_mfma_f32_16x16x32_bf16 v[20:23], v[132:135], v[188:191], v[20:23]
	v_mfma_f32_16x16x32_bf16 v[12:15], v[140:143], v[188:191], v[12:15]
	s_setprio 0
	s_setprio 1
	v_mfma_f32_16x16x32_bf16 v[48:51], v[144:147], v[160:163], 0
	v_mfma_f32_16x16x32_bf16 v[40:43], v[152:155], v[160:163], 0
	v_mfma_f32_16x16x32_bf16 v[32:35], v[144:147], v[168:171], 0
	v_mfma_f32_16x16x32_bf16 v[24:27], v[152:155], v[168:171], 0
	v_mfma_f32_16x16x32_bf16 v[16:19], v[144:147], v[176:179], 0
	v_mfma_f32_16x16x32_bf16 v[8:11], v[152:155], v[176:179], 0
	v_mfma_f32_16x16x32_bf16 v[4:7], v[144:147], v[184:187], 0
	v_mfma_f32_16x16x32_bf16 v[0:3], v[152:155], v[184:187], 0
	v_mfma_f32_16x16x32_bf16 v[48:51], v[148:151], v[164:167], v[48:51]
	v_mfma_f32_16x16x32_bf16 v[40:43], v[156:159], v[164:167], v[40:43]
	v_mfma_f32_16x16x32_bf16 v[32:35], v[148:151], v[172:175], v[32:35]
	v_mfma_f32_16x16x32_bf16 v[24:27], v[156:159], v[172:175], v[24:27]
	v_mfma_f32_16x16x32_bf16 v[16:19], v[148:151], v[180:183], v[16:19]
	v_mfma_f32_16x16x32_bf16 v[8:11], v[156:159], v[180:183], v[8:11]
	v_mfma_f32_16x16x32_bf16 v[4:7], v[148:151], v[188:191], v[4:7]
	v_mfma_f32_16x16x32_bf16 v[0:3], v[156:159], v[188:191], v[0:3]
	s_setprio 0
	s_barrier
	s_add_i32 s22, 0, 0x18000
	s_add_i32 s23, 0, 0x1c000
	v_add_u32_e32 v140, s22, v240
	v_add_u32_e32 v156, s23, v240
	ds_read_b128 v[128:131], v140
	ds_read_b128 v[132:135], v140 offset:1024
	ds_read_b128 v[136:139], v140 offset:2048
	ds_read_b128 v[140:143], v140 offset:3072
	ds_read_b128 v[144:147], v156
	ds_read_b128 v[148:151], v156 offset:1024
	ds_read_b128 v[152:155], v156 offset:2048
	ds_read_b128 v[156:159], v156 offset:3072
	s_add_u32 s20, s84, 0x40000
	s_addc_u32 s21, s85, 0
	s_mov_b32 m0, s66
	v_lshl_add_u64 v[212:213], s[20:21], 0, v[192:193]
	ds_read_b128 v[160:163], v244 offset:32768
	ds_read_b128 v[164:167], v244 offset:33792
	ds_read_b128 v[168:171], v244 offset:34816
	ds_read_b128 v[172:175], v244 offset:35840
	ds_read_b128 v[176:179], v244 offset:36864
	ds_read_b128 v[180:183], v244 offset:37888
	ds_read_b128 v[184:187], v244 offset:38912
	ds_read_b128 v[188:191], v244 offset:39936
	global_load_lds_dwordx4 v[212:213], off
	v_lshl_add_u64 v[212:213], s[20:21], 0, v[196:197]
	s_mov_b32 m0, s67
	s_nop 0
	global_load_lds_dwordx4 v[212:213], off
	s_waitcnt vmcnt(8)
	s_waitcnt lgkmcnt(0)
	s_barrier
; #define PG8_STAGE(bufoff, gbase, voff) do { _Pragma("unroll") for (int _i = 0; _i < 2; ++_i) \
;         __builtin_amdgcn_global_load_lds((const unsigned*)((const char*)(gbase) + (voff)[_i]), (PG8_LAS unsigned*)(lds + (bufoff) + ldsw + _i * 8192), 16, 0, 0); } while (0)
; #define PG8_LDA(dst, b, h) do { _Pragma("unroll") for (int m = 0; m < 4; ++m) _Pragma("unroll") for (int k = 0; k < 2; ++k) dst[m][k] = *(const PG8_LAS bf16x8*)(lds + PG8_SA(b, h) + aoff + m * 2048 + k * 1024); } while (0)
; #define PG8_MMA(ai, bj, At, Bt) do { __builtin_amdgcn_s_setprio(1); _Pragma("unroll") for (int m = 0; m < 4; ++m) _Pragma("unroll") for (int n = 0; n < 2; ++n) _Pragma("unroll") for (int k = 0; k < 2; ++k) \
;         acc[ai][bj][m][n] = __builtin_amdgcn_mfma_f32_16x16x32_bf16(Bt[n][k], At[m][k], acc[ai][bj][m][n], 0, 0, 0); __builtin_amdgcn_s_setprio(0); } while (0)
; #define PG8_WAIT_V(n) asm volatile("s_waitcnt vmcnt(" #n ")" ::: "memory")
; #define PG8_WAIT_L(n) asm volatile("s_waitcnt lgkmcnt(" #n ")" ::: "memory")
; #define PG8_BAR __builtin_amdgcn_s_barrier()
; #define PG8_SCHED __builtin_amdgcn_sched_barrier(0)
; template <class Epi, class Sched, bool ALIGN_EPI = false, bool SP2 = false>
; __device__ __forceinline__ void gemm_phase(PG8_LAS unsigned char* lds, const Gemm g, const Sched& S, const Epi& E) {
;     ...
;         for (int t = 0; t < nt; t += 2) {
;     ...
;             PG8_WAIT_V(8); PG8_WAIT_L(0); PG8_BAR; PG8_MMA(0, 0, At, B0); if (whole) PG8_MMA(0, 1, At, B1); PG8_BAR; PG8_SCHED;
;             PG8_LDA(At, 1, 1); PG8_STAGE(PG8_SB(1, 0), b3, voffB); PG8_STAGE(PG8_SB(1, 1), b3 + hstepB, voffB); PG8_STAGE(PG8_SA(1, 0), a3, voffA);
;             PG8_WAIT_V(8); PG8_WAIT_L(0); PG8_BAR; if (whole) { PG8_MMA(1, 0, At, B0); PG8_MMA(1, 1, At, B1); } PG8_BAR; PG8_SCHED;
	s_setprio 1
	s_waitcnt lgkmcnt(0)
	v_mfma_f32_16x16x32_bf16 v[124:127], v[128:131], v[160:163], v[124:127]
	v_mfma_f32_16x16x32_bf16 v[120:123], v[136:139], v[160:163], v[120:123]
	v_mfma_f32_16x16x32_bf16 v[116:119], v[128:131], v[168:171], v[116:119]
	v_mfma_f32_16x16x32_bf16 v[108:111], v[136:139], v[168:171], v[108:111]
	v_mfma_f32_16x16x32_bf16 v[100:103], v[128:131], v[176:179], v[100:103]
	v_mfma_f32_16x16x32_bf16 v[92:95], v[136:139], v[176:179], v[92:95]
	v_mfma_f32_16x16x32_bf16 v[84:87], v[128:131], v[184:187], v[84:87]
	v_mfma_f32_16x16x32_bf16 v[76:79], v[136:139], v[184:187], v[76:79]
	v_mfma_f32_16x16x32_bf16 v[124:127], v[132:135], v[164:167], v[124:127]
	v_mfma_f32_16x16x32_bf16 v[120:123], v[140:143], v[164:167], v[120:123]
	v_mfma_f32_16x16x32_bf16 v[116:119], v[132:135], v[172:175], v[116:119]
	v_mfma_f32_16x16x32_bf16 v[108:111], v[140:143], v[172:175], v[108:111]
	v_mfma_f32_16x16x32_bf16 v[100:103], v[132:135], v[180:183], v[100:103]
	v_mfma_f32_16x16x32_bf16 v[92:95], v[140:143], v[180:183], v[92:95]
	v_mfma_f32_16x16x32_bf16 v[84:87], v[132:135], v[188:191], v[84:87]
	v_mfma_f32_16x16x32_bf16 v[76:79], v[140:143], v[188:191], v[76:79]
	s_setprio 0
	s_setprio 1
	v_mfma_f32_16x16x32_bf16 v[112:115], v[144:147], v[160:163], v[112:115]
	v_mfma_f32_16x16x32_bf16 v[104:107], v[152:155], v[160:163], v[104:107]
	v_mfma_f32_16x16x32_bf16 v[96:99], v[144:147], v[168:171], v[96:99]
	v_mfma_f32_16x16x32_bf16 v[88:91], v[152:155], v[168:171], v[88:91]
	v_mfma_f32_16x16x32_bf16 v[80:83], v[144:147], v[176:179], v[80:83]
	v_mfma_f32_16x16x32_bf16 v[72:75], v[152:155], v[176:179], v[72:75]
	v_mfma_f32_16x16x32_bf16 v[68:71], v[144:147], v[184:187], v[68:71]
	v_mfma_f32_16x16x32_bf16 v[64:67], v[152:155], v[184:187], v[64:67]
	v_mfma_f32_16x16x32_bf16 v[112:115], v[148:151], v[164:167], v[112:115]
	v_mfma_f32_16x16x32_bf16 v[104:107], v[156:159], v[164:167], v[104:107]
	v_mfma_f32_16x16x32_bf16 v[96:99], v[148:151], v[172:175], v[96:99]
	v_mfma_f32_16x16x32_bf16 v[88:91], v[156:159], v[172:175], v[88:91]
	v_mfma_f32_16x16x32_bf16 v[80:83], v[148:151], v[180:183], v[80:83]
	v_mfma_f32_16x16x32_bf16 v[72:75], v[156:159], v[180:183], v[72:75]
	v_mfma_f32_16x16x32_bf16 v[68:71], v[148:151], v[188:191], v[68:71]
	v_mfma_f32_16x16x32_bf16 v[64:67], v[156:159], v[188:191], v[64:67]
	s_setprio 0
	s_barrier
	s_add_i32 s20, s22, s8
	v_lshl_add_u64 v[204:205], v[204:205], 0, s[52:53]
	s_mov_b32 m0, s20
	ds_read_b128 v[160:163], v244 offset:49152
	ds_read_b128 v[164:167], v244 offset:50176
	ds_read_b128 v[168:171], v244 offset:51200
	ds_read_b128 v[172:175], v244 offset:52224
	ds_read_b128 v[176:179], v244 offset:53248
	ds_read_b128 v[180:183], v244 offset:54272
	ds_read_b128 v[184:187], v244 offset:55296
	ds_read_b128 v[188:191], v244 offset:56320
	global_load_lds_dwordx4 v[204:205], off
	s_add_i32 m0, s20, 0x2000
	s_add_u32 s6, s6, 0x40080
	v_lshl_add_u64 v[204:205], v[206:207], 0, s[52:53]
	s_addc_u32 s7, s7, 0
	s_add_i32 s20, s23, s8
	global_load_lds_dwordx4 v[204:205], off
	v_lshl_add_u64 v[204:205], s[6:7], 0, v[194:195]
	s_mov_b32 m0, s20
	s_nop 0
	global_load_lds_dwordx4 v[204:205], off
	v_lshl_add_u64 v[204:205], s[6:7], 0, v[198:199]
	s_add_i32 m0, s20, 0x2000
	s_nop 0
	global_load_lds_dwordx4 v[204:205], off
	v_lshl_add_u64 v[204:205], v[208:209], 0, s[52:53]
	s_mov_b32 m0, s79
	s_nop 0
	global_load_lds_dwordx4 v[204:205], off
	v_lshl_add_u64 v[204:205], v[210:211], 0, s[52:53]
	s_mov_b32 m0, s81
	s_nop 0
	global_load_lds_dwordx4 v[204:205], off
	s_waitcnt vmcnt(8)
	s_waitcnt lgkmcnt(0)
	s_barrier
	s_setprio 1
	s_waitcnt lgkmcnt(0)
	v_mfma_f32_16x16x32_bf16 v[60:63], v[128:131], v[160:163], v[60:63]
	v_mfma_f32_16x16x32_bf16 v[56:59], v[136:139], v[160:163], v[56:59]
	v_mfma_f32_16x16x32_bf16 v[52:55], v[128:131], v[168:171], v[52:55]
	v_mfma_f32_16x16x32_bf16 v[44:47], v[136:139], v[168:171], v[44:47]
	v_mfma_f32_16x16x32_bf16 v[36:39], v[128:131], v[176:179], v[36:39]
	v_mfma_f32_16x16x32_bf16 v[28:31], v[136:139], v[176:179], v[28:31]
	v_mfma_f32_16x16x32_bf16 v[20:23], v[128:131], v[184:187], v[20:23]
	v_mfma_f32_16x16x32_bf16 v[12:15], v[136:139], v[184:187], v[12:15]
	v_mfma_f32_16x16x32_bf16 v[60:63], v[132:135], v[164:167], v[60:63]
	v_mfma_f32_16x16x32_bf16 v[56:59], v[140:143], v[164:167], v[56:59]
	v_mfma_f32_16x16x32_bf16 v[52:55], v[132:135], v[172:175], v[52:55]
	v_mfma_f32_16x16x32_bf16 v[44:47], v[140:143], v[172:175], v[44:47]
	v_mfma_f32_16x16x32_bf16 v[36:39], v[132:135], v[180:183], v[36:39]
	v_mfma_f32_16x16x32_bf16 v[28:31], v[140:143], v[180:183], v[28:31]
	v_mfma_f32_16x16x32_bf16 v[20:23], v[132:135], v[188:191], v[20:23]
	v_mfma_f32_16x16x32_bf16 v[12:15], v[140:143], v[188:191], v[12:15]
	s_setprio 0
	s_setprio 1
	v_mfma_f32_16x16x32_bf16 v[48:51], v[144:147], v[160:163], v[48:51]
	v_mfma_f32_16x16x32_bf16 v[40:43], v[152:155], v[160:163], v[40:43]
	v_mfma_f32_16x16x32_bf16 v[32:35], v[144:147], v[168:171], v[32:35]
	v_mfma_f32_16x16x32_bf16 v[24:27], v[152:155], v[168:171], v[24:27]
	v_mfma_f32_16x16x32_bf16 v[16:19], v[144:147], v[176:179], v[16:19]
	v_mfma_f32_16x16x32_bf16 v[8:11], v[152:155], v[176:179], v[8:11]
	v_mfma_f32_16x16x32_bf16 v[4:7], v[144:147], v[184:187], v[4:7]
	v_mfma_f32_16x16x32_bf16 v[0:3], v[152:155], v[184:187], v[0:3]
	v_mfma_f32_16x16x32_bf16 v[48:51], v[148:151], v[164:167], v[48:51]
	v_mfma_f32_16x16x32_bf16 v[40:43], v[156:159], v[164:167], v[40:43]
	v_mfma_f32_16x16x32_bf16 v[32:35], v[148:151], v[172:175], v[32:35]
	v_mfma_f32_16x16x32_bf16 v[24:27], v[156:159], v[172:175], v[24:27]
	v_mfma_f32_16x16x32_bf16 v[16:19], v[148:151], v[180:183], v[16:19]
	v_mfma_f32_16x16x32_bf16 v[8:11], v[156:159], v[180:183], v[8:11]
	v_mfma_f32_16x16x32_bf16 v[4:7], v[148:151], v[188:191], v[4:7]
	v_mfma_f32_16x16x32_bf16 v[0:3], v[156:159], v[188:191], v[0:3]
	s_setprio 0
	s_barrier
	s_add_u32 s82, s82, 0x100
	s_addc_u32 s83, s83, 0
	s_add_u32 s17, s17, 0x100
	s_addc_u32 s18, s18, 0
	s_cmp_ge_u32 s19, s9
	s_mov_b32 s6, s19
	s_cbranch_scc0 .LBB0_383
	s_branch .Lpeel_exit_out0

; #define PG8_STAGE(bufoff, gbase, voff) do { _Pragma("unroll") for (int _i = 0; _i < 2; ++_i) \
;         __builtin_amdgcn_global_load_lds((const unsigned*)((const char*)(gbase) + (voff)[_i]), (PG8_LAS unsigned*)(lds + (bufoff) + ldsw + _i * 8192), 16, 0, 0); } while (0)
; #define PG8_LDA(dst, b, h) do { _Pragma("unroll") for (int m = 0; m < 4; ++m) _Pragma("unroll") for (int k = 0; k < 2; ++k) dst[m][k] = *(const PG8_LAS bf16x8*)(lds + PG8_SA(b, h) + aoff + m * 2048 + k * 1024); } while (0)
; #define PG8_LDB(dst, b, h) do { _Pragma("unroll") for (int n = 0; n < 2; ++n) _Pragma("unroll") for (int k = 0; k < 2; ++k) dst[n][k] = *(const PG8_LAS bf16x8*)(lds + PG8_SB(b, h) + boff + n * 2048 + k * 1024); } while (0)
; #define PG8_WAIT_V(n) asm volatile("s_waitcnt vmcnt(" #n ")" ::: "memory")
; #define PG8_WAIT_L(n) asm volatile("s_waitcnt lgkmcnt(" #n ")" ::: "memory")
; #define PG8_BAR __builtin_amdgcn_s_barrier()
;     __host__ __device__ __forceinline__ bool next(int i, Unit& u) const { const long L = (long)i * G + c; if (L >= nwg) return false; map((int)L, u); return true; }
; template <class Epi, class Sched, bool ALIGN_EPI = false, bool SP2 = false>
; __device__ __forceinline__ void gemm_phase(PG8_LAS unsigned char* lds, const Gemm g, const Sched& S, const Epi& E) {
;     ...
;         const char* nA = has_next ? (const char*)g.A + (size_t)nxt.pm * tstepA + (size_t)(nxt.k0 >> 6) * kstepA + (nxt.qa > 0 ? hstepA : (size_t)0) : cA; const char* nB = has_next ? (const char*)g.Bt + (size_t)nxt.pn * tstepB + (size_t)nxt.k0 * 2 + (nxt.qb > 0 ? hstepB : (size_t)0) : cB;
;         const bool whole = cur.qa < 0;
;         const int nt = cur.nt;
;         for (int t = 0; t < nt; t += 2) {
;             const bool last = (t == nt - 2);
;             const char* a1 = cA + (size_t)(t + 1) * kstepA;
;             const char* a2 = last ? nA : cA + (size_t)(t + 2) * kstepA; const char* b2 = last ? nB : cB + (size_t)(t + 2) * kstep;
;             const char* a3 = a2 + kstepA; const char* b3 = b2 + kstep;
;             if (last && has_next) S.a_ready(nxt);
;             if constexpr (SP2) {
;             PG8_LDB(B0, 0, 0); PG8_LDB(B1, 0, 1); PG8_SCHED; PG8_LDA(At, 0, 0); PG8_STAGE(PG8_SA(1, 1), a1 + hstepA, voffA);
;             PG8_WAIT_V(8); PG8_WAIT_L(0); PG8_BAR; PG8_MMA(0, 0, At, B0); if (whole) PG8_MMA(0, 1, At, B1); PG8_BAR; PG8_SCHED;
.LBB0_590:
	s_add_i32 s7, s15, s6
	s_ashr_i32 s6, s7, 31
	s_lshr_b32 s6, s6, 28
	s_add_i32 s15, s7, s6
	s_ashr_i32 s6, s15, 4
	s_lshl_b32 s16, s6, 2
	s_sub_i32 s6, 64, s16
	s_min_i32 s17, s6, 4
	s_abs_i32 s18, s17
	v_cvt_f32_u32_e32 v0, s18
	s_sub_i32 s24, 0, s18
	s_and_b32 s15, s15, -16
	s_sub_i32 s7, s7, s15
	v_rcp_iflag_f32_e32 v0, v0
	s_abs_i32 s15, s7
	s_max_i32 s19, s14, 0x100
	s_xor_b32 s21, s7, s17
	v_mul_f32_e32 v0, 0x4f7ffffe, v0
	v_cvt_u32_f32_e32 v0, v0
	s_add_i32 s20, s19, 0xffffff00
	s_ashr_i32 s21, s21, 31
	s_mov_b32 s6, 0
	v_readfirstlane_b32 s25, v0
	s_mul_i32 s24, s24, s25
	s_mul_hi_u32 s24, s25, s24
	s_add_i32 s25, s25, s24
	s_mul_hi_u32 s24, s15, s25
	s_mul_i32 s25, s24, s18
	s_sub_i32 s15, s15, s25
	s_add_i32 s25, s24, 1
	s_sub_i32 s26, s15, s18
	s_cmp_ge_u32 s15, s18
	s_cselect_b32 s24, s25, s24
	s_cselect_b32 s15, s26, s15
	s_add_i32 s25, s24, 1
	s_cmp_ge_u32 s15, s18
	s_cselect_b32 s15, s25, s24
	s_xor_b32 s15, s15, s21
	s_sub_i32 s15, s15, s21
	s_mul_i32 s17, s15, s17
	s_sub_i32 s7, s7, s17
	s_add_i32 s7, s16, s7
	s_lshr_b32 s16, s20, 5
	s_and_b32 s87, s19, 7
	s_add_i32 s18, s16, 64
	s_and_b64 s[16:17], s[50:51], exec
	s_cselect_b32 s52, s7, s18
	s_bfe_u32 s7, s19, 0x20003
	s_and_b64 s[16:17], s[50:51], exec
	s_cselect_b32 s54, s15, s7
	s_lshl_b32 s7, s87, 9
	s_and_b64 s[16:17], s[50:51], exec
	s_cselect_b32 s7, 0, s7
	s_ashr_i32 s53, s52, 31
	s_lshl_b64 s[16:17], s[52:53], 21
	s_add_u32 s15, s34, s16
	s_addc_u32 s16, s35, s17
	s_lshl_b32 s17, s7, 9
	s_add_u32 s56, s15, s17
	s_addc_u32 s57, s16, 0
	s_ashr_i32 s55, s54, 31
	s_lshl_b64 s[16:17], s[54:55], 21
	s_add_u32 s15, s40, s16
	s_addc_u32 s16, s41, s17
	s_lshl_b32 s7, s7, 1
	s_add_u32 s58, s15, s7
	s_addc_u32 s59, s16, 0
	s_cmpk_lt_i32 s14, 0x180
	s_cselect_b64 s[60:61], -1, 0
	s_and_b64 s[14:15], s[60:61], exec
	s_cselect_b32 s14, s57, s67
	s_cselect_b32 s15, s56, s66
	s_cselect_b32 s16, s59, s77
	s_cselect_b32 s17, s58, s76
	s_add_i32 s18, s9, -2
	s_add_u32 s19, s76, 0x100
	s_addc_u32 s20, s77, 0
	s_waitcnt lgkmcnt(0)
	ds_read_b128 v[128:131], v242
	ds_read_b128 v[132:135], v242 offset:1024
	ds_read_b128 v[136:139], v242 offset:2048
	ds_read_b128 v[140:143], v242 offset:3072
	ds_read_b128 v[144:147], v243
	ds_read_b128 v[148:151], v243 offset:1024
	ds_read_b128 v[152:155], v243 offset:2048
	ds_read_b128 v[156:159], v243 offset:3072
	s_add_i32 s21, s6, 2
	s_add_u32 s76, s66, 0x10000
	s_addc_u32 s77, s67, 0
	s_cmp_eq_u32 s18, s6
	s_cselect_b32 s80, s15, s76
	s_cselect_b32 s81, s14, s77
	s_cselect_b32 s78, s17, s19
	s_cselect_b32 s79, s16, s20
	s_add_u32 s6, s80, 0x8000
	s_addc_u32 s7, s81, 0
	v_lshl_add_u64 v[204:205], s[66:67], 0, v[200:201]
	s_add_i32 m0, s28, 0xc000
	ds_read_b128 v[160:163], v244
	ds_read_b128 v[164:167], v244 offset:1024
	ds_read_b128 v[168:171], v244 offset:2048
	ds_read_b128 v[172:175], v244 offset:3072
	ds_read_b128 v[176:179], v244 offset:4096
	ds_read_b128 v[180:183], v244 offset:5120
	ds_read_b128 v[184:187], v244 offset:6144
	ds_read_b128 v[188:191], v244 offset:7168
	global_load_lds_dwordx4 v[204:205], off
	v_lshl_add_u64 v[204:205], s[66:67], 0, v[202:203]
	s_add_i32 m0, s28, 0xe000
	s_nop 0
	global_load_lds_dwordx4 v[204:205], off
	s_waitcnt vmcnt(24)
	s_waitcnt lgkmcnt(0)
	s_barrier
	s_setprio 1
	s_waitcnt lgkmcnt(0)
	v_mfma_f32_16x16x32_bf16 v[124:127], v[128:131], v[160:163], 0
	v_mfma_f32_16x16x32_bf16 v[120:123], v[136:139], v[160:163], 0
	v_mfma_f32_16x16x32_bf16 v[116:119], v[128:131], v[168:171], 0
	v_mfma_f32_16x16x32_bf16 v[108:111], v[136:139], v[168:171], 0
	v_mfma_f32_16x16x32_bf16 v[100:103], v[128:131], v[176:179], 0
	v_mfma_f32_16x16x32_bf16 v[92:95], v[136:139], v[176:179], 0
	v_mfma_f32_16x16x32_bf16 v[84:87], v[128:131], v[184:187], 0
	v_mfma_f32_16x16x32_bf16 v[76:79], v[136:139], v[184:187], 0
	v_mfma_f32_16x16x32_bf16 v[124:127], v[132:135], v[164:167], v[124:127]
	v_mfma_f32_16x16x32_bf16 v[120:123], v[140:143], v[164:167], v[120:123]
	v_mfma_f32_16x16x32_bf16 v[116:119], v[132:135], v[172:175], v[116:119]
	v_mfma_f32_16x16x32_bf16 v[108:111], v[140:143], v[172:175], v[108:111]
	v_mfma_f32_16x16x32_bf16 v[100:103], v[132:135], v[180:183], v[100:103]
	v_mfma_f32_16x16x32_bf16 v[92:95], v[140:143], v[180:183], v[92:95]
	v_mfma_f32_16x16x32_bf16 v[84:87], v[132:135], v[188:191], v[84:87]
	v_mfma_f32_16x16x32_bf16 v[76:79], v[140:143], v[188:191], v[76:79]
	s_setprio 0
	s_setprio 1
	v_mfma_f32_16x16x32_bf16 v[112:115], v[144:147], v[160:163], 0
	v_mfma_f32_16x16x32_bf16 v[104:107], v[152:155], v[160:163], 0
	v_mfma_f32_16x16x32_bf16 v[96:99], v[144:147], v[168:171], 0
	v_mfma_f32_16x16x32_bf16 v[88:91], v[152:155], v[168:171], 0
	v_mfma_f32_16x16x32_bf16 v[80:83], v[144:147], v[176:179], 0
	v_mfma_f32_16x16x32_bf16 v[72:75], v[152:155], v[176:179], 0
	v_mfma_f32_16x16x32_bf16 v[68:71], v[144:147], v[184:187], 0
	v_mfma_f32_16x16x32_bf16 v[64:67], v[152:155], v[184:187], 0
	v_mfma_f32_16x16x32_bf16 v[112:115], v[148:151], v[164:167], v[112:115]
	v_mfma_f32_16x16x32_bf16 v[104:107], v[156:159], v[164:167], v[104:107]
	v_mfma_f32_16x16x32_bf16 v[96:99], v[148:151], v[172:175], v[96:99]
	v_mfma_f32_16x16x32_bf16 v[88:91], v[156:159], v[172:175], v[88:91]
	v_mfma_f32_16x16x32_bf16 v[80:83], v[148:151], v[180:183], v[80:83]
	v_mfma_f32_16x16x32_bf16 v[72:75], v[156:159], v[180:183], v[72:75]
	v_mfma_f32_16x16x32_bf16 v[68:71], v[148:151], v[188:191], v[68:71]
	v_mfma_f32_16x16x32_bf16 v[64:67], v[156:159], v[188:191], v[64:67]
	s_setprio 0
	s_barrier
; #define PG8_STAGE(bufoff, gbase, voff) do { _Pragma("unroll") for (int _i = 0; _i < 2; ++_i) \
;         __builtin_amdgcn_global_load_lds((const unsigned*)((const char*)(gbase) + (voff)[_i]), (PG8_LAS unsigned*)(lds + (bufoff) + ldsw + _i * 8192), 16, 0, 0); } while (0)
; #define PG8_LDA(dst, b, h) do { _Pragma("unroll") for (int m = 0; m < 4; ++m) _Pragma("unroll") for (int k = 0; k < 2; ++k) dst[m][k] = *(const PG8_LAS bf16x8*)(lds + PG8_SA(b, h) + aoff + m * 2048 + k * 1024); } while (0)
; #define PG8_LDB(dst, b, h) do { _Pragma("unroll") for (int n = 0; n < 2; ++n) _Pragma("unroll") for (int k = 0; k < 2; ++k) dst[n][k] = *(const PG8_LAS bf16x8*)(lds + PG8_SB(b, h) + boff + n * 2048 + k * 1024); } while (0)
; #define PG8_MMA(ai, bj, At, Bt) do { __builtin_amdgcn_s_setprio(1); _Pragma("unroll") for (int m = 0; m < 4; ++m) _Pragma("unroll") for (int n = 0; n < 2; ++n) _Pragma("unroll") for (int k = 0; k < 2; ++k) \
;         acc[ai][bj][m][n] = __builtin_amdgcn_mfma_f32_16x16x32_bf16(Bt[n][k], At[m][k], acc[ai][bj][m][n], 0, 0, 0); __builtin_amdgcn_s_setprio(0); } while (0)
; #define PG8_WAIT_V(n) asm volatile("s_waitcnt vmcnt(" #n ")" ::: "memory")
; #define PG8_WAIT_L(n) asm volatile("s_waitcnt lgkmcnt(" #n ")" ::: "memory")
; #define PG8_BAR __builtin_amdgcn_s_barrier()
; #define PG8_SCHED __builtin_amdgcn_sched_barrier(0)
; template <class Epi, class Sched, bool ALIGN_EPI = false, bool SP2 = false>
; __device__ __forceinline__ void gemm_phase(PG8_LAS unsigned char* lds, const Gemm g, const Sched& S, const Epi& E) {
;     ...
;             PG8_LDA(At, 0, 1); PG8_STAGE(PG8_SB(0, 0), b2, voffB); PG8_STAGE(PG8_SB(0, 1), b2 + hstepB, voffB); PG8_STAGE(PG8_SA(0, 0), a2, voffA);
;             PG8_WAIT_V(8); PG8_WAIT_L(0); PG8_BAR; if (whole) { PG8_MMA(1, 0, At, B0); PG8_MMA(1, 1, At, B1); } PG8_BAR; PG8_SCHED;
;             PG8_LDB(B0, 1, 0); PG8_LDB(B1, 1, 1); PG8_SCHED; PG8_LDA(At, 1, 0); PG8_STAGE(PG8_SA(0, 1), a2 + hstepA, voffA);
;             PG8_WAIT_V(8); PG8_WAIT_L(0); PG8_BAR; PG8_MMA(0, 0, At, B0); if (whole) PG8_MMA(0, 1, At, B1); PG8_BAR; PG8_SCHED;
	s_add_i32 s24, s84, s8
	v_lshl_add_u64 v[204:205], s[78:79], 0, v[194:195]
	s_mov_b32 m0, s24
	ds_read_b128 v[160:163], v244 offset:16384
	ds_read_b128 v[164:167], v244 offset:17408
	ds_read_b128 v[168:171], v244 offset:18432
	ds_read_b128 v[172:175], v244 offset:19456
	ds_read_b128 v[176:179], v244 offset:20480
	ds_read_b128 v[180:183], v244 offset:21504
	ds_read_b128 v[184:187], v244 offset:22528
	ds_read_b128 v[188:191], v244 offset:23552
	global_load_lds_dwordx4 v[204:205], off
	s_add_i32 m0, s24, 0x2000
	s_add_u32 s24, s78, 0x100000
	v_lshl_add_u64 v[206:207], s[78:79], 0, v[198:199]
	s_addc_u32 s25, s79, 0
	s_add_i32 s26, s85, s8
	global_load_lds_dwordx4 v[206:207], off
	v_lshl_add_u64 v[208:209], s[24:25], 0, v[194:195]
	s_mov_b32 m0, s26
	s_nop 0
	global_load_lds_dwordx4 v[208:209], off
	v_lshl_add_u64 v[208:209], s[24:25], 0, v[198:199]
	s_add_i32 m0, s26, 0x2000
	s_nop 0
	global_load_lds_dwordx4 v[208:209], off
	v_lshl_add_u64 v[208:209], s[80:81], 0, v[192:193]
	s_mov_b32 m0, s28
	s_nop 0
	global_load_lds_dwordx4 v[208:209], off
	v_lshl_add_u64 v[208:209], s[80:81], 0, v[196:197]
	s_mov_b32 m0, s29
	s_nop 0
	global_load_lds_dwordx4 v[208:209], off
	s_waitcnt vmcnt(24)
	s_waitcnt lgkmcnt(0)
	s_barrier
	s_setprio 1
	s_waitcnt lgkmcnt(0)
	v_mfma_f32_16x16x32_bf16 v[60:63], v[128:131], v[160:163], 0
	v_mfma_f32_16x16x32_bf16 v[56:59], v[136:139], v[160:163], 0
	v_mfma_f32_16x16x32_bf16 v[52:55], v[128:131], v[168:171], 0
	v_mfma_f32_16x16x32_bf16 v[44:47], v[136:139], v[168:171], 0
	v_mfma_f32_16x16x32_bf16 v[36:39], v[128:131], v[176:179], 0
	v_mfma_f32_16x16x32_bf16 v[28:31], v[136:139], v[176:179], 0
	v_mfma_f32_16x16x32_bf16 v[20:23], v[128:131], v[184:187], 0
	v_mfma_f32_16x16x32_bf16 v[12:15], v[136:139], v[184:187], 0
	v_mfma_f32_16x16x32_bf16 v[60:63], v[132:135], v[164:167], v[60:63]
	v_mfma_f32_16x16x32_bf16 v[56:59], v[140:143], v[164:167], v[56:59]
	v_mfma_f32_16x16x32_bf16 v[52:55], v[132:135], v[172:175], v[52:55]
	v_mfma_f32_16x16x32_bf16 v[44:47], v[140:143], v[172:175], v[44:47]
	v_mfma_f32_16x16x32_bf16 v[36:39], v[132:135], v[180:183], v[36:39]
	v_mfma_f32_16x16x32_bf16 v[28:31], v[140:143], v[180:183], v[28:31]
	v_mfma_f32_16x16x32_bf16 v[20:23], v[132:135], v[188:191], v[20:23]
	v_mfma_f32_16x16x32_bf16 v[12:15], v[140:143], v[188:191], v[12:15]
	s_setprio 0
	s_setprio 1
	v_mfma_f32_16x16x32_bf16 v[48:51], v[144:147], v[160:163], 0
	v_mfma_f32_16x16x32_bf16 v[40:43], v[152:155], v[160:163], 0
	v_mfma_f32_16x16x32_bf16 v[32:35], v[144:147], v[168:171], 0
	v_mfma_f32_16x16x32_bf16 v[24:27], v[152:155], v[168:171], 0
	v_mfma_f32_16x16x32_bf16 v[16:19], v[144:147], v[176:179], 0
	v_mfma_f32_16x16x32_bf16 v[8:11], v[152:155], v[176:179], 0
	v_mfma_f32_16x16x32_bf16 v[4:7], v[144:147], v[184:187], 0
	v_mfma_f32_16x16x32_bf16 v[0:3], v[152:155], v[184:187], 0
	v_mfma_f32_16x16x32_bf16 v[48:51], v[148:151], v[164:167], v[48:51]
	v_mfma_f32_16x16x32_bf16 v[40:43], v[156:159], v[164:167], v[40:43]
	v_mfma_f32_16x16x32_bf16 v[32:35], v[148:151], v[172:175], v[32:35]
	v_mfma_f32_16x16x32_bf16 v[24:27], v[156:159], v[172:175], v[24:27]
	v_mfma_f32_16x16x32_bf16 v[16:19], v[148:151], v[180:183], v[16:19]
	v_mfma_f32_16x16x32_bf16 v[8:11], v[156:159], v[180:183], v[8:11]
	v_mfma_f32_16x16x32_bf16 v[4:7], v[148:151], v[188:191], v[4:7]
	v_mfma_f32_16x16x32_bf16 v[0:3], v[156:159], v[188:191], v[0:3]
	s_setprio 0
	s_barrier
	s_add_i32 s26, 0, 0x18000
	s_add_i32 s27, 0, 0x1c000
	v_add_u32_e32 v140, s26, v240
	v_add_u32_e32 v156, s27, v240
	ds_read_b128 v[128:131], v140
	ds_read_b128 v[132:135], v140 offset:1024
	ds_read_b128 v[136:139], v140 offset:2048
	ds_read_b128 v[140:143], v140 offset:3072
	ds_read_b128 v[144:147], v156
	ds_read_b128 v[148:151], v156 offset:1024
	ds_read_b128 v[152:155], v156 offset:2048
	ds_read_b128 v[156:159], v156 offset:3072
	s_add_u32 s24, s80, 0x2000
	s_addc_u32 s25, s81, 0
	s_mov_b32 m0, s63
	v_lshl_add_u64 v[208:209], s[24:25], 0, v[192:193]
	ds_read_b128 v[160:163], v244 offset:32768
	ds_read_b128 v[164:167], v244 offset:33792
	ds_read_b128 v[168:171], v244 offset:34816
	ds_read_b128 v[172:175], v244 offset:35840
	ds_read_b128 v[176:179], v244 offset:36864
	ds_read_b128 v[180:183], v244 offset:37888
	ds_read_b128 v[184:187], v244 offset:38912
	ds_read_b128 v[188:191], v244 offset:39936
	global_load_lds_dwordx4 v[208:209], off
	v_lshl_add_u64 v[208:209], s[24:25], 0, v[196:197]
	s_mov_b32 m0, s65
	s_nop 0
	global_load_lds_dwordx4 v[208:209], off
	s_waitcnt vmcnt(8)
	s_waitcnt lgkmcnt(0)
	s_barrier
; #define PG8_STAGE(bufoff, gbase, voff) do { _Pragma("unroll") for (int _i = 0; _i < 2; ++_i) \
;         __builtin_amdgcn_global_load_lds((const unsigned*)((const char*)(gbase) + (voff)[_i]), (PG8_LAS unsigned*)(lds + (bufoff) + ldsw + _i * 8192), 16, 0, 0); } while (0)
; #define PG8_LDA(dst, b, h) do { _Pragma("unroll") for (int m = 0; m < 4; ++m) _Pragma("unroll") for (int k = 0; k < 2; ++k) dst[m][k] = *(const PG8_LAS bf16x8*)(lds + PG8_SA(b, h) + aoff + m * 2048 + k * 1024); } while (0)
; #define PG8_MMA(ai, bj, At, Bt) do { __builtin_amdgcn_s_setprio(1); _Pragma("unroll") for (int m = 0; m < 4; ++m) _Pragma("unroll") for (int n = 0; n < 2; ++n) _Pragma("unroll") for (int k = 0; k < 2; ++k) \
;         acc[ai][bj][m][n] = __builtin_amdgcn_mfma_f32_16x16x32_bf16(Bt[n][k], At[m][k], acc[ai][bj][m][n], 0, 0, 0); __builtin_amdgcn_s_setprio(0); } while (0)
; #define PG8_WAIT_V(n) asm volatile("s_waitcnt vmcnt(" #n ")" ::: "memory")
; #define PG8_WAIT_L(n) asm volatile("s_waitcnt lgkmcnt(" #n ")" ::: "memory")
; #define PG8_BAR __builtin_amdgcn_s_barrier()
; #define PG8_SCHED __builtin_amdgcn_sched_barrier(0)
; template <class Epi, class Sched, bool ALIGN_EPI = false, bool SP2 = false>
; __device__ __forceinline__ void gemm_phase(PG8_LAS unsigned char* lds, const Gemm g, const Sched& S, const Epi& E) {
;     ...
;         for (int t = 0; t < nt; t += 2) {
;     ...
;             PG8_WAIT_V(8); PG8_WAIT_L(0); PG8_BAR; PG8_MMA(0, 0, At, B0); if (whole) PG8_MMA(0, 1, At, B1); PG8_BAR; PG8_SCHED;
;             PG8_LDA(At, 1, 1); PG8_STAGE(PG8_SB(1, 0), b3, voffB); PG8_STAGE(PG8_SB(1, 1), b3 + hstepB, voffB); PG8_STAGE(PG8_SA(1, 0), a3, voffA);
;             PG8_WAIT_V(8); PG8_WAIT_L(0); PG8_BAR; if (whole) { PG8_MMA(1, 0, At, B0); PG8_MMA(1, 1, At, B1); } PG8_BAR; PG8_SCHED;
	s_setprio 1
	s_waitcnt lgkmcnt(0)
	v_mfma_f32_16x16x32_bf16 v[124:127], v[128:131], v[160:163], v[124:127]
	v_mfma_f32_16x16x32_bf16 v[120:123], v[136:139], v[160:163], v[120:123]
	v_mfma_f32_16x16x32_bf16 v[116:119], v[128:131], v[168:171], v[116:119]
	v_mfma_f32_16x16x32_bf16 v[108:111], v[136:139], v[168:171], v[108:111]
	v_mfma_f32_16x16x32_bf16 v[100:103], v[128:131], v[176:179], v[100:103]
	v_mfma_f32_16x16x32_bf16 v[92:95], v[136:139], v[176:179], v[92:95]
	v_mfma_f32_16x16x32_bf16 v[84:87], v[128:131], v[184:187], v[84:87]
	v_mfma_f32_16x16x32_bf16 v[76:79], v[136:139], v[184:187], v[76:79]
	v_mfma_f32_16x16x32_bf16 v[124:127], v[132:135], v[164:167], v[124:127]
	v_mfma_f32_16x16x32_bf16 v[120:123], v[140:143], v[164:167], v[120:123]
	v_mfma_f32_16x16x32_bf16 v[116:119], v[132:135], v[172:175], v[116:119]
	v_mfma_f32_16x16x32_bf16 v[108:111], v[140:143], v[172:175], v[108:111]
	v_mfma_f32_16x16x32_bf16 v[100:103], v[132:135], v[180:183], v[100:103]
	v_mfma_f32_16x16x32_bf16 v[92:95], v[140:143], v[180:183], v[92:95]
	v_mfma_f32_16x16x32_bf16 v[84:87], v[132:135], v[188:191], v[84:87]
	v_mfma_f32_16x16x32_bf16 v[76:79], v[140:143], v[188:191], v[76:79]
	s_setprio 0
	s_setprio 1
	v_mfma_f32_16x16x32_bf16 v[112:115], v[144:147], v[160:163], v[112:115]
	v_mfma_f32_16x16x32_bf16 v[104:107], v[152:155], v[160:163], v[104:107]
	v_mfma_f32_16x16x32_bf16 v[96:99], v[144:147], v[168:171], v[96:99]
	v_mfma_f32_16x16x32_bf16 v[88:91], v[152:155], v[168:171], v[88:91]
	v_mfma_f32_16x16x32_bf16 v[80:83], v[144:147], v[176:179], v[80:83]
	v_mfma_f32_16x16x32_bf16 v[72:75], v[152:155], v[176:179], v[72:75]
	v_mfma_f32_16x16x32_bf16 v[68:71], v[144:147], v[184:187], v[68:71]
	v_mfma_f32_16x16x32_bf16 v[64:67], v[152:155], v[184:187], v[64:67]
	v_mfma_f32_16x16x32_bf16 v[112:115], v[148:151], v[164:167], v[112:115]
	v_mfma_f32_16x16x32_bf16 v[104:107], v[156:159], v[164:167], v[104:107]
	v_mfma_f32_16x16x32_bf16 v[96:99], v[148:151], v[172:175], v[96:99]
	v_mfma_f32_16x16x32_bf16 v[88:91], v[156:159], v[172:175], v[88:91]
	v_mfma_f32_16x16x32_bf16 v[80:83], v[148:151], v[180:183], v[80:83]
	v_mfma_f32_16x16x32_bf16 v[72:75], v[156:159], v[180:183], v[72:75]
	v_mfma_f32_16x16x32_bf16 v[68:71], v[148:151], v[188:191], v[68:71]
	v_mfma_f32_16x16x32_bf16 v[64:67], v[156:159], v[188:191], v[64:67]
	s_setprio 0
	s_barrier
	s_add_i32 s24, s26, s8
	v_lshl_add_u64 v[204:205], v[204:205], 0, s[42:43]
	s_mov_b32 m0, s24
	ds_read_b128 v[160:163], v244 offset:49152
	ds_read_b128 v[164:167], v244 offset:50176
	ds_read_b128 v[168:171], v244 offset:51200
	ds_read_b128 v[172:175], v244 offset:52224
	ds_read_b128 v[176:179], v244 offset:53248
	ds_read_b128 v[180:183], v244 offset:54272
	ds_read_b128 v[184:187], v244 offset:55296
	ds_read_b128 v[188:191], v244 offset:56320
	global_load_lds_dwordx4 v[204:205], off
	s_add_i32 m0, s24, 0x2000
	s_add_u32 s24, s78, 0x100080
	v_lshl_add_u64 v[204:205], v[206:207], 0, s[42:43]
	s_addc_u32 s25, s79, 0
	s_add_i32 s26, s27, s8
	global_load_lds_dwordx4 v[204:205], off
	v_lshl_add_u64 v[204:205], s[24:25], 0, v[194:195]
	s_mov_b32 m0, s26
	s_nop 0
	global_load_lds_dwordx4 v[204:205], off
	v_lshl_add_u64 v[204:205], s[24:25], 0, v[198:199]
	s_add_i32 m0, s26, 0x2000
	s_nop 0
	global_load_lds_dwordx4 v[204:205], off
	v_lshl_add_u64 v[204:205], s[6:7], 0, v[192:193]
	s_mov_b32 m0, s82
	s_nop 0
	global_load_lds_dwordx4 v[204:205], off
	v_lshl_add_u64 v[204:205], s[6:7], 0, v[196:197]
	s_mov_b32 m0, s83
	s_nop 0
	global_load_lds_dwordx4 v[204:205], off
	s_waitcnt vmcnt(8)
	s_waitcnt lgkmcnt(0)
	s_barrier
	s_setprio 1
	s_waitcnt lgkmcnt(0)
	v_mfma_f32_16x16x32_bf16 v[60:63], v[128:131], v[160:163], v[60:63]
	v_mfma_f32_16x16x32_bf16 v[56:59], v[136:139], v[160:163], v[56:59]
	v_mfma_f32_16x16x32_bf16 v[52:55], v[128:131], v[168:171], v[52:55]
	v_mfma_f32_16x16x32_bf16 v[44:47], v[136:139], v[168:171], v[44:47]
	v_mfma_f32_16x16x32_bf16 v[36:39], v[128:131], v[176:179], v[36:39]
	v_mfma_f32_16x16x32_bf16 v[28:31], v[136:139], v[176:179], v[28:31]
	v_mfma_f32_16x16x32_bf16 v[20:23], v[128:131], v[184:187], v[20:23]
	v_mfma_f32_16x16x32_bf16 v[12:15], v[136:139], v[184:187], v[12:15]
	v_mfma_f32_16x16x32_bf16 v[60:63], v[132:135], v[164:167], v[60:63]
	v_mfma_f32_16x16x32_bf16 v[56:59], v[140:143], v[164:167], v[56:59]
	v_mfma_f32_16x16x32_bf16 v[52:55], v[132:135], v[172:175], v[52:55]
	v_mfma_f32_16x16x32_bf16 v[44:47], v[140:143], v[172:175], v[44:47]
	v_mfma_f32_16x16x32_bf16 v[36:39], v[132:135], v[180:183], v[36:39]
	v_mfma_f32_16x16x32_bf16 v[28:31], v[140:143], v[180:183], v[28:31]
	v_mfma_f32_16x16x32_bf16 v[20:23], v[132:135], v[188:191], v[20:23]
	v_mfma_f32_16x16x32_bf16 v[12:15], v[140:143], v[188:191], v[12:15]
	s_setprio 0
	s_setprio 1
	v_mfma_f32_16x16x32_bf16 v[48:51], v[144:147], v[160:163], v[48:51]
	v_mfma_f32_16x16x32_bf16 v[40:43], v[152:155], v[160:163], v[40:43]
	v_mfma_f32_16x16x32_bf16 v[32:35], v[144:147], v[168:171], v[32:35]
	v_mfma_f32_16x16x32_bf16 v[24:27], v[152:155], v[168:171], v[24:27]
	v_mfma_f32_16x16x32_bf16 v[16:19], v[144:147], v[176:179], v[16:19]
	v_mfma_f32_16x16x32_bf16 v[8:11], v[152:155], v[176:179], v[8:11]
	v_mfma_f32_16x16x32_bf16 v[4:7], v[144:147], v[184:187], v[4:7]
	v_mfma_f32_16x16x32_bf16 v[0:3], v[152:155], v[184:187], v[0:3]
	v_mfma_f32_16x16x32_bf16 v[48:51], v[148:151], v[164:167], v[48:51]
	v_mfma_f32_16x16x32_bf16 v[40:43], v[156:159], v[164:167], v[40:43]
	v_mfma_f32_16x16x32_bf16 v[32:35], v[148:151], v[172:175], v[32:35]
	v_mfma_f32_16x16x32_bf16 v[24:27], v[156:159], v[172:175], v[24:27]
	v_mfma_f32_16x16x32_bf16 v[16:19], v[148:151], v[180:183], v[16:19]
	v_mfma_f32_16x16x32_bf16 v[8:11], v[156:159], v[180:183], v[8:11]
	v_mfma_f32_16x16x32_bf16 v[4:7], v[148:151], v[188:191], v[4:7]
	v_mfma_f32_16x16x32_bf16 v[0:3], v[156:159], v[188:191], v[0:3]
	s_setprio 0
	s_barrier
	s_add_u32 s19, s19, 0x100
	s_addc_u32 s20, s20, 0
	s_cmp_ge_u32 s21, s9
	s_mov_b64 s[66:67], s[76:77]
	s_mov_b32 s6, s21
	s_cbranch_scc0 .LBB0_591
	s_branch .Lpeel_exit_down0

; #define PG8_STAGE(bufoff, gbase, voff) do { _Pragma("unroll") for (int _i = 0; _i < 2; ++_i) \
;         __builtin_amdgcn_global_load_lds((const unsigned*)((const char*)(gbase) + (voff)[_i]), (PG8_LAS unsigned*)(lds + (bufoff) + ldsw + _i * 8192), 16, 0, 0); } while (0)
; #define PG8_LDA(dst, b, h) do { _Pragma("unroll") for (int m = 0; m < 4; ++m) _Pragma("unroll") for (int k = 0; k < 2; ++k) dst[m][k] = *(const PG8_LAS bf16x8*)(lds + PG8_SA(b, h) + aoff + m * 2048 + k * 1024); } while (0)
; #define PG8_LDB(dst, b, h) do { _Pragma("unroll") for (int n = 0; n < 2; ++n) _Pragma("unroll") for (int k = 0; k < 2; ++k) dst[n][k] = *(const PG8_LAS bf16x8*)(lds + PG8_SB(b, h) + boff + n * 2048 + k * 1024); } while (0)
; #define PG8_WAIT_V(n) asm volatile("s_waitcnt vmcnt(" #n ")" ::: "memory")
; #define PG8_WAIT_L(n) asm volatile("s_waitcnt lgkmcnt(" #n ")" ::: "memory")
; #define PG8_BAR __builtin_amdgcn_s_barrier()
;     __host__ __device__ __forceinline__ bool next(int i, Unit& u) const { const long L = (long)i * G + c; if (L >= nwg) return false; map((int)L, u); return true; }
; template <class Epi, class Sched, bool ALIGN_EPI = false, bool SP2 = false>
; __device__ __forceinline__ void gemm_phase(PG8_LAS unsigned char* lds, const Gemm g, const Sched& S, const Epi& E) {
;     ...
;         const char* nA = has_next ? (const char*)g.A + (size_t)nxt.pm * tstepA + (size_t)(nxt.k0 >> 6) * kstepA + (nxt.qa > 0 ? hstepA : (size_t)0) : cA; const char* nB = has_next ? (const char*)g.Bt + (size_t)nxt.pn * tstepB + (size_t)nxt.k0 * 2 + (nxt.qb > 0 ? hstepB : (size_t)0) : cB;
;         const bool whole = cur.qa < 0;
;         const int nt = cur.nt;
;         for (int t = 0; t < nt; t += 2) {
;             const bool last = (t == nt - 2);
;             const char* a1 = cA + (size_t)(t + 1) * kstepA;
;             const char* a2 = last ? nA : cA + (size_t)(t + 2) * kstepA; const char* b2 = last ? nB : cB + (size_t)(t + 2) * kstep;
;             const char* a3 = a2 + kstepA; const char* b3 = b2 + kstep;
;             if (last && has_next) S.a_ready(nxt);
;             if constexpr (SP2) {
;             PG8_LDB(B0, 0, 0); PG8_LDB(B1, 0, 1); PG8_SCHED; PG8_LDA(At, 0, 0); PG8_STAGE(PG8_SA(1, 1), a1 + hstepA, voffA);
;             PG8_WAIT_V(8); PG8_WAIT_L(0); PG8_BAR; PG8_MMA(0, 0, At, B0); if (whole) PG8_MMA(0, 1, At, B1); PG8_BAR; PG8_SCHED;
.LBB0_1079:
	s_add_i32 s7, s38, s6
	s_ashr_i32 s6, s7, 31
	s_lshr_b32 s6, s6, 28
	s_add_i32 s38, s7, s6
	s_ashr_i32 s6, s38, 4
	s_lshl_b32 s39, s6, 2
	s_sub_i32 s6, 64, s39
	s_min_i32 s40, s6, 4
	s_abs_i32 s41, s40
	v_cvt_f32_u32_e32 v0, s41
	s_sub_i32 s45, 0, s41
	s_and_b32 s38, s38, -16
	s_sub_i32 s7, s7, s38
	v_rcp_iflag_f32_e32 v0, v0
	s_abs_i32 s38, s7
	s_max_i32 s42, s46, 0x100
	s_xor_b32 s44, s7, s40
	v_mul_f32_e32 v0, 0x4f7ffffe, v0
	v_cvt_u32_f32_e32 v0, v0
	s_add_i32 s43, s42, 0xffffff00
	s_ashr_i32 s44, s44, 31
	s_mov_b32 s6, 0
	v_readfirstlane_b32 s47, v0
	s_mul_i32 s45, s45, s47
	s_mul_hi_u32 s45, s47, s45
	s_add_i32 s47, s47, s45
	s_mul_hi_u32 s45, s38, s47
	s_mul_i32 s47, s45, s41
	s_sub_i32 s38, s38, s47
	s_add_i32 s47, s45, 1
	s_sub_i32 s85, s38, s41
	s_cmp_ge_u32 s38, s41
	s_cselect_b32 s45, s47, s45
	s_cselect_b32 s38, s85, s38
	s_add_i32 s47, s45, 1
	s_cmp_ge_u32 s38, s41
	s_cselect_b32 s38, s47, s45
	s_xor_b32 s38, s38, s44
	s_sub_i32 s44, s38, s44
	s_mul_i32 s38, s44, s40
	s_sub_i32 s7, s7, s38
	s_lshr_b32 s38, s43, 4
	s_add_i32 s7, s39, s7
	s_and_b32 s85, s42, 3
	s_add_i32 s40, s38, 64
	s_and_b64 s[38:39], s[26:27], exec
	s_cselect_b32 s38, s7, s40
	s_bfe_u32 s7, s42, 0x20002
	s_and_b64 s[40:41], s[26:27], exec
	s_cselect_b32 s40, s44, s7
	s_lshl_b32 s7, s85, 9
	s_and_b64 s[42:43], s[26:27], exec
	s_cselect_b32 s7, 0, s7
	s_ashr_i32 s39, s38, 31
	s_lshl_b64 s[42:43], s[38:39], 19
	s_add_u32 s39, s36, s42
	s_addc_u32 s41, s37, s43
	s_add_u32 s42, s39, s7
	s_addc_u32 s43, s41, 0
	s_ashr_i32 s41, s40, 31
	s_lshl_b64 s[44:45], s[40:41], 19
	s_add_u32 s39, s28, s44
	s_addc_u32 s41, s29, s45
	s_add_u32 s44, s39, s7
	s_addc_u32 s45, s41, 0
	s_cmpk_lt_i32 s46, 0x140
	s_cselect_b64 s[46:47], -1, 0
	s_and_b64 s[86:87], s[46:47], exec
	s_cselect_b32 s39, s43, s53
	s_cselect_b32 s41, s42, s52
	s_cselect_b32 s86, s45, s55
	s_cselect_b32 s87, s44, s54
	s_add_i32 s90, s9, -2
	s_add_u32 s52, s52, 0x40080
	s_addc_u32 s53, s53, 0
	s_add_u32 s91, s54, 0x100
	s_addc_u32 s92, s55, 0
	s_waitcnt lgkmcnt(0)
	ds_read_b128 v[128:131], v242
	ds_read_b128 v[132:135], v242 offset:1024
	ds_read_b128 v[136:139], v242 offset:2048
	ds_read_b128 v[140:143], v242 offset:3072
	ds_read_b128 v[144:147], v243
	ds_read_b128 v[148:151], v243 offset:1024
	ds_read_b128 v[152:155], v243 offset:2048
	ds_read_b128 v[156:159], v243 offset:3072
	s_add_i32 s93, s6, 2
	s_add_u32 s7, s52, 0xfffc0080
	s_addc_u32 s54, s53, -1
	s_cmp_eq_u32 s90, s6
	s_cselect_b32 s6, s87, s91
	s_cselect_b32 s55, s39, s54
	s_cselect_b32 s54, s41, s7
	s_cselect_b32 s7, s86, s92
	v_lshl_add_u64 v[204:205], s[52:53], 0, v[200:201]
	s_add_i32 m0, s49, 0xc000
	ds_read_b128 v[160:163], v244
	ds_read_b128 v[164:167], v244 offset:1024
	ds_read_b128 v[168:171], v244 offset:2048
	ds_read_b128 v[172:175], v244 offset:3072
	ds_read_b128 v[176:179], v244 offset:4096
	ds_read_b128 v[180:183], v244 offset:5120
	ds_read_b128 v[184:187], v244 offset:6144
	ds_read_b128 v[188:191], v244 offset:7168
	global_load_lds_dwordx4 v[204:205], off
	v_lshl_add_u64 v[204:205], s[52:53], 0, v[202:203]
	s_add_i32 m0, s49, 0xe000
	s_nop 0
	global_load_lds_dwordx4 v[204:205], off
	s_waitcnt vmcnt(24)
	s_waitcnt lgkmcnt(0)
	s_barrier
	s_setprio 1
	s_waitcnt lgkmcnt(0)
	v_mfma_f32_16x16x32_bf16 v[124:127], v[128:131], v[160:163], 0
	v_mfma_f32_16x16x32_bf16 v[120:123], v[136:139], v[160:163], 0
	v_mfma_f32_16x16x32_bf16 v[116:119], v[128:131], v[168:171], 0
	v_mfma_f32_16x16x32_bf16 v[108:111], v[136:139], v[168:171], 0
	v_mfma_f32_16x16x32_bf16 v[100:103], v[128:131], v[176:179], 0
	v_mfma_f32_16x16x32_bf16 v[92:95], v[136:139], v[176:179], 0
	v_mfma_f32_16x16x32_bf16 v[84:87], v[128:131], v[184:187], 0
	v_mfma_f32_16x16x32_bf16 v[76:79], v[136:139], v[184:187], 0
	v_mfma_f32_16x16x32_bf16 v[124:127], v[132:135], v[164:167], v[124:127]
	v_mfma_f32_16x16x32_bf16 v[120:123], v[140:143], v[164:167], v[120:123]
	v_mfma_f32_16x16x32_bf16 v[116:119], v[132:135], v[172:175], v[116:119]
	v_mfma_f32_16x16x32_bf16 v[108:111], v[140:143], v[172:175], v[108:111]
	v_mfma_f32_16x16x32_bf16 v[100:103], v[132:135], v[180:183], v[100:103]
	v_mfma_f32_16x16x32_bf16 v[92:95], v[140:143], v[180:183], v[92:95]
	v_mfma_f32_16x16x32_bf16 v[84:87], v[132:135], v[188:191], v[84:87]
	v_mfma_f32_16x16x32_bf16 v[76:79], v[140:143], v[188:191], v[76:79]
	s_setprio 0
	s_setprio 1
	v_mfma_f32_16x16x32_bf16 v[112:115], v[144:147], v[160:163], 0
	v_mfma_f32_16x16x32_bf16 v[104:107], v[152:155], v[160:163], 0
	v_mfma_f32_16x16x32_bf16 v[96:99], v[144:147], v[168:171], 0
	v_mfma_f32_16x16x32_bf16 v[88:91], v[152:155], v[168:171], 0
	v_mfma_f32_16x16x32_bf16 v[80:83], v[144:147], v[176:179], 0
	v_mfma_f32_16x16x32_bf16 v[72:75], v[152:155], v[176:179], 0
	v_mfma_f32_16x16x32_bf16 v[68:71], v[144:147], v[184:187], 0
	v_mfma_f32_16x16x32_bf16 v[64:67], v[152:155], v[184:187], 0
	v_mfma_f32_16x16x32_bf16 v[112:115], v[148:151], v[164:167], v[112:115]
	v_mfma_f32_16x16x32_bf16 v[104:107], v[156:159], v[164:167], v[104:107]
	v_mfma_f32_16x16x32_bf16 v[96:99], v[148:151], v[172:175], v[96:99]
	v_mfma_f32_16x16x32_bf16 v[88:91], v[156:159], v[172:175], v[88:91]
	v_mfma_f32_16x16x32_bf16 v[80:83], v[148:151], v[180:183], v[80:83]
	v_mfma_f32_16x16x32_bf16 v[72:75], v[156:159], v[180:183], v[72:75]
	v_mfma_f32_16x16x32_bf16 v[68:71], v[148:151], v[188:191], v[68:71]
	v_mfma_f32_16x16x32_bf16 v[64:67], v[156:159], v[188:191], v[64:67]
	s_setprio 0
	s_barrier
; #define PG8_STAGE(bufoff, gbase, voff) do { _Pragma("unroll") for (int _i = 0; _i < 2; ++_i) \
;         __builtin_amdgcn_global_load_lds((const unsigned*)((const char*)(gbase) + (voff)[_i]), (PG8_LAS unsigned*)(lds + (bufoff) + ldsw + _i * 8192), 16, 0, 0); } while (0)
; #define PG8_LDA(dst, b, h) do { _Pragma("unroll") for (int m = 0; m < 4; ++m) _Pragma("unroll") for (int k = 0; k < 2; ++k) dst[m][k] = *(const PG8_LAS bf16x8*)(lds + PG8_SA(b, h) + aoff + m * 2048 + k * 1024); } while (0)
; #define PG8_LDB(dst, b, h) do { _Pragma("unroll") for (int n = 0; n < 2; ++n) _Pragma("unroll") for (int k = 0; k < 2; ++k) dst[n][k] = *(const PG8_LAS bf16x8*)(lds + PG8_SB(b, h) + boff + n * 2048 + k * 1024); } while (0)
; #define PG8_MMA(ai, bj, At, Bt) do { __builtin_amdgcn_s_setprio(1); _Pragma("unroll") for (int m = 0; m < 4; ++m) _Pragma("unroll") for (int n = 0; n < 2; ++n) _Pragma("unroll") for (int k = 0; k < 2; ++k) \
;         acc[ai][bj][m][n] = __builtin_amdgcn_mfma_f32_16x16x32_bf16(Bt[n][k], At[m][k], acc[ai][bj][m][n], 0, 0, 0); __builtin_amdgcn_s_setprio(0); } while (0)
; #define PG8_WAIT_V(n) asm volatile("s_waitcnt vmcnt(" #n ")" ::: "memory")
; #define PG8_WAIT_L(n) asm volatile("s_waitcnt lgkmcnt(" #n ")" ::: "memory")
; #define PG8_BAR __builtin_amdgcn_s_barrier()
; #define PG8_SCHED __builtin_amdgcn_sched_barrier(0)
; template <class Epi, class Sched, bool ALIGN_EPI = false, bool SP2 = false>
; __device__ __forceinline__ void gemm_phase(PG8_LAS unsigned char* lds, const Gemm g, const Sched& S, const Epi& E) {
;     ...
;             PG8_LDA(At, 0, 1); PG8_STAGE(PG8_SB(0, 0), b2, voffB); PG8_STAGE(PG8_SB(0, 1), b2 + hstepB, voffB); PG8_STAGE(PG8_SA(0, 0), a2, voffA);
;             PG8_WAIT_V(8); PG8_WAIT_L(0); PG8_BAR; if (whole) { PG8_MMA(1, 0, At, B0); PG8_MMA(1, 1, At, B1); } PG8_BAR; PG8_SCHED;
;             PG8_LDB(B0, 1, 0); PG8_LDB(B1, 1, 1); PG8_SCHED; PG8_LDA(At, 1, 0); PG8_STAGE(PG8_SA(0, 1), a2 + hstepA, voffA);
;             PG8_WAIT_V(8); PG8_WAIT_L(0); PG8_BAR; PG8_MMA(0, 0, At, B0); if (whole) PG8_MMA(0, 1, At, B1); PG8_BAR; PG8_SCHED;
	s_add_i32 s94, s60, s8
	v_lshl_add_u64 v[204:205], s[6:7], 0, v[194:195]
	s_mov_b32 m0, s94
	ds_read_b128 v[160:163], v244 offset:16384
	ds_read_b128 v[164:167], v244 offset:17408
	ds_read_b128 v[168:171], v244 offset:18432
	ds_read_b128 v[172:175], v244 offset:19456
	ds_read_b128 v[176:179], v244 offset:20480
	ds_read_b128 v[180:183], v244 offset:21504
	ds_read_b128 v[184:187], v244 offset:22528
	ds_read_b128 v[188:191], v244 offset:23552
	global_load_lds_dwordx4 v[204:205], off
	s_add_i32 m0, s94, 0x2000
	s_add_u32 s94, s6, 0x40000
	v_lshl_add_u64 v[206:207], s[6:7], 0, v[198:199]
	s_addc_u32 s95, s7, 0
	s_add_i32 s96, s61, s8
	global_load_lds_dwordx4 v[206:207], off
	v_lshl_add_u64 v[208:209], s[94:95], 0, v[194:195]
	s_mov_b32 m0, s96
	v_lshl_add_u64 v[210:211], s[54:55], 0, v[196:197]
	global_load_lds_dwordx4 v[208:209], off
	v_lshl_add_u64 v[208:209], s[94:95], 0, v[198:199]
	s_add_i32 m0, s96, 0x2000
	s_nop 0
	global_load_lds_dwordx4 v[208:209], off
	v_lshl_add_u64 v[208:209], s[54:55], 0, v[192:193]
	s_mov_b32 m0, s49
	s_nop 0
	global_load_lds_dwordx4 v[208:209], off
	s_mov_b32 m0, s51
	s_nop 0
	global_load_lds_dwordx4 v[210:211], off
	s_waitcnt vmcnt(24)
	s_waitcnt lgkmcnt(0)
	s_barrier
	s_setprio 1
	s_waitcnt lgkmcnt(0)
	v_mfma_f32_16x16x32_bf16 v[60:63], v[128:131], v[160:163], 0
	v_mfma_f32_16x16x32_bf16 v[56:59], v[136:139], v[160:163], 0
	v_mfma_f32_16x16x32_bf16 v[52:55], v[128:131], v[168:171], 0
	v_mfma_f32_16x16x32_bf16 v[44:47], v[136:139], v[168:171], 0
	v_mfma_f32_16x16x32_bf16 v[36:39], v[128:131], v[176:179], 0
	v_mfma_f32_16x16x32_bf16 v[28:31], v[136:139], v[176:179], 0
	v_mfma_f32_16x16x32_bf16 v[20:23], v[128:131], v[184:187], 0
	v_mfma_f32_16x16x32_bf16 v[12:15], v[136:139], v[184:187], 0
	v_mfma_f32_16x16x32_bf16 v[60:63], v[132:135], v[164:167], v[60:63]
	v_mfma_f32_16x16x32_bf16 v[56:59], v[140:143], v[164:167], v[56:59]
	v_mfma_f32_16x16x32_bf16 v[52:55], v[132:135], v[172:175], v[52:55]
	v_mfma_f32_16x16x32_bf16 v[44:47], v[140:143], v[172:175], v[44:47]
	v_mfma_f32_16x16x32_bf16 v[36:39], v[132:135], v[180:183], v[36:39]
	v_mfma_f32_16x16x32_bf16 v[28:31], v[140:143], v[180:183], v[28:31]
	v_mfma_f32_16x16x32_bf16 v[20:23], v[132:135], v[188:191], v[20:23]
	v_mfma_f32_16x16x32_bf16 v[12:15], v[140:143], v[188:191], v[12:15]
	s_setprio 0
	s_setprio 1
	v_mfma_f32_16x16x32_bf16 v[48:51], v[144:147], v[160:163], 0
	v_mfma_f32_16x16x32_bf16 v[40:43], v[152:155], v[160:163], 0
	v_mfma_f32_16x16x32_bf16 v[32:35], v[144:147], v[168:171], 0
	v_mfma_f32_16x16x32_bf16 v[24:27], v[152:155], v[168:171], 0
	v_mfma_f32_16x16x32_bf16 v[16:19], v[144:147], v[176:179], 0
	v_mfma_f32_16x16x32_bf16 v[8:11], v[152:155], v[176:179], 0
	v_mfma_f32_16x16x32_bf16 v[4:7], v[144:147], v[184:187], 0
	v_mfma_f32_16x16x32_bf16 v[0:3], v[152:155], v[184:187], 0
	v_mfma_f32_16x16x32_bf16 v[48:51], v[148:151], v[164:167], v[48:51]
	v_mfma_f32_16x16x32_bf16 v[40:43], v[156:159], v[164:167], v[40:43]
	v_mfma_f32_16x16x32_bf16 v[32:35], v[148:151], v[172:175], v[32:35]
	v_mfma_f32_16x16x32_bf16 v[24:27], v[156:159], v[172:175], v[24:27]
	v_mfma_f32_16x16x32_bf16 v[16:19], v[148:151], v[180:183], v[16:19]
	v_mfma_f32_16x16x32_bf16 v[8:11], v[156:159], v[180:183], v[8:11]
	v_mfma_f32_16x16x32_bf16 v[4:7], v[148:151], v[188:191], v[4:7]
	v_mfma_f32_16x16x32_bf16 v[0:3], v[156:159], v[188:191], v[0:3]
	s_setprio 0
	s_barrier
	s_add_i32 s94, 0, 0x18000
	s_add_i32 s95, 0, 0x1c000
	v_add_u32_e32 v140, s94, v240
	v_add_u32_e32 v156, s95, v240
	ds_read_b128 v[128:131], v140
	ds_read_b128 v[132:135], v140 offset:1024
	ds_read_b128 v[136:139], v140 offset:2048
	ds_read_b128 v[140:143], v140 offset:3072
	ds_read_b128 v[144:147], v156
	ds_read_b128 v[148:151], v156 offset:1024
	ds_read_b128 v[152:155], v156 offset:2048
	ds_read_b128 v[156:159], v156 offset:3072
	s_add_u32 s54, s54, 0x40000
	s_addc_u32 s55, s55, 0
	s_mov_b32 m0, s56
	v_lshl_add_u64 v[212:213], s[54:55], 0, v[192:193]
	ds_read_b128 v[160:163], v244 offset:32768
	ds_read_b128 v[164:167], v244 offset:33792
	ds_read_b128 v[168:171], v244 offset:34816
	ds_read_b128 v[172:175], v244 offset:35840
	ds_read_b128 v[176:179], v244 offset:36864
	ds_read_b128 v[180:183], v244 offset:37888
	ds_read_b128 v[184:187], v244 offset:38912
	ds_read_b128 v[188:191], v244 offset:39936
	global_load_lds_dwordx4 v[212:213], off
	v_lshl_add_u64 v[212:213], s[54:55], 0, v[196:197]
	s_mov_b32 m0, s57
	s_nop 0
	global_load_lds_dwordx4 v[212:213], off
	s_waitcnt vmcnt(8)
	s_waitcnt lgkmcnt(0)
	s_barrier
; #define PG8_STAGE(bufoff, gbase, voff) do { _Pragma("unroll") for (int _i = 0; _i < 2; ++_i) \
;         __builtin_amdgcn_global_load_lds((const unsigned*)((const char*)(gbase) + (voff)[_i]), (PG8_LAS unsigned*)(lds + (bufoff) + ldsw + _i * 8192), 16, 0, 0); } while (0)
; #define PG8_LDA(dst, b, h) do { _Pragma("unroll") for (int m = 0; m < 4; ++m) _Pragma("unroll") for (int k = 0; k < 2; ++k) dst[m][k] = *(const PG8_LAS bf16x8*)(lds + PG8_SA(b, h) + aoff + m * 2048 + k * 1024); } while (0)
; #define PG8_MMA(ai, bj, At, Bt) do { __builtin_amdgcn_s_setprio(1); _Pragma("unroll") for (int m = 0; m < 4; ++m) _Pragma("unroll") for (int n = 0; n < 2; ++n) _Pragma("unroll") for (int k = 0; k < 2; ++k) \
;         acc[ai][bj][m][n] = __builtin_amdgcn_mfma_f32_16x16x32_bf16(Bt[n][k], At[m][k], acc[ai][bj][m][n], 0, 0, 0); __builtin_amdgcn_s_setprio(0); } while (0)
; #define PG8_WAIT_V(n) asm volatile("s_waitcnt vmcnt(" #n ")" ::: "memory")
; #define PG8_WAIT_L(n) asm volatile("s_waitcnt lgkmcnt(" #n ")" ::: "memory")
; #define PG8_BAR __builtin_amdgcn_s_barrier()
; #define PG8_SCHED __builtin_amdgcn_sched_barrier(0)
; template <class Epi, class Sched, bool ALIGN_EPI = false, bool SP2 = false>
; __device__ __forceinline__ void gemm_phase(PG8_LAS unsigned char* lds, const Gemm g, const Sched& S, const Epi& E) {
;     ...
;         for (int t = 0; t < nt; t += 2) {
;     ...
;             PG8_WAIT_V(8); PG8_WAIT_L(0); PG8_BAR; PG8_MMA(0, 0, At, B0); if (whole) PG8_MMA(0, 1, At, B1); PG8_BAR; PG8_SCHED;
;             PG8_LDA(At, 1, 1); PG8_STAGE(PG8_SB(1, 0), b3, voffB); PG8_STAGE(PG8_SB(1, 1), b3 + hstepB, voffB); PG8_STAGE(PG8_SA(1, 0), a3, voffA);
;             PG8_WAIT_V(8); PG8_WAIT_L(0); PG8_BAR; if (whole) { PG8_MMA(1, 0, At, B0); PG8_MMA(1, 1, At, B1); } PG8_BAR; PG8_SCHED;
	s_setprio 1
	s_waitcnt lgkmcnt(0)
	v_mfma_f32_16x16x32_bf16 v[124:127], v[128:131], v[160:163], v[124:127]
	v_mfma_f32_16x16x32_bf16 v[120:123], v[136:139], v[160:163], v[120:123]
	v_mfma_f32_16x16x32_bf16 v[116:119], v[128:131], v[168:171], v[116:119]
	v_mfma_f32_16x16x32_bf16 v[108:111], v[136:139], v[168:171], v[108:111]
	v_mfma_f32_16x16x32_bf16 v[100:103], v[128:131], v[176:179], v[100:103]
	v_mfma_f32_16x16x32_bf16 v[92:95], v[136:139], v[176:179], v[92:95]
	v_mfma_f32_16x16x32_bf16 v[84:87], v[128:131], v[184:187], v[84:87]
	v_mfma_f32_16x16x32_bf16 v[76:79], v[136:139], v[184:187], v[76:79]
	v_mfma_f32_16x16x32_bf16 v[124:127], v[132:135], v[164:167], v[124:127]
	v_mfma_f32_16x16x32_bf16 v[120:123], v[140:143], v[164:167], v[120:123]
	v_mfma_f32_16x16x32_bf16 v[116:119], v[132:135], v[172:175], v[116:119]
	v_mfma_f32_16x16x32_bf16 v[108:111], v[140:143], v[172:175], v[108:111]
	v_mfma_f32_16x16x32_bf16 v[100:103], v[132:135], v[180:183], v[100:103]
	v_mfma_f32_16x16x32_bf16 v[92:95], v[140:143], v[180:183], v[92:95]
	v_mfma_f32_16x16x32_bf16 v[84:87], v[132:135], v[188:191], v[84:87]
	v_mfma_f32_16x16x32_bf16 v[76:79], v[140:143], v[188:191], v[76:79]
	s_setprio 0
	s_setprio 1
	v_mfma_f32_16x16x32_bf16 v[112:115], v[144:147], v[160:163], v[112:115]
	v_mfma_f32_16x16x32_bf16 v[104:107], v[152:155], v[160:163], v[104:107]
	v_mfma_f32_16x16x32_bf16 v[96:99], v[144:147], v[168:171], v[96:99]
	v_mfma_f32_16x16x32_bf16 v[88:91], v[152:155], v[168:171], v[88:91]
	v_mfma_f32_16x16x32_bf16 v[80:83], v[144:147], v[176:179], v[80:83]
	v_mfma_f32_16x16x32_bf16 v[72:75], v[152:155], v[176:179], v[72:75]
	v_mfma_f32_16x16x32_bf16 v[68:71], v[144:147], v[184:187], v[68:71]
	v_mfma_f32_16x16x32_bf16 v[64:67], v[152:155], v[184:187], v[64:67]
	v_mfma_f32_16x16x32_bf16 v[112:115], v[148:151], v[164:167], v[112:115]
	v_mfma_f32_16x16x32_bf16 v[104:107], v[156:159], v[164:167], v[104:107]
	v_mfma_f32_16x16x32_bf16 v[96:99], v[148:151], v[172:175], v[96:99]
	v_mfma_f32_16x16x32_bf16 v[88:91], v[156:159], v[172:175], v[88:91]
	v_mfma_f32_16x16x32_bf16 v[80:83], v[148:151], v[180:183], v[80:83]
	v_mfma_f32_16x16x32_bf16 v[72:75], v[156:159], v[180:183], v[72:75]
	v_mfma_f32_16x16x32_bf16 v[68:71], v[148:151], v[188:191], v[68:71]
	v_mfma_f32_16x16x32_bf16 v[64:67], v[156:159], v[188:191], v[64:67]
	s_setprio 0
	s_barrier
	s_add_i32 s54, s94, s8
	v_lshl_add_u64 v[204:205], v[204:205], 0, s[20:21]
	s_mov_b32 m0, s54
	ds_read_b128 v[160:163], v244 offset:49152
	ds_read_b128 v[164:167], v244 offset:50176
	ds_read_b128 v[168:171], v244 offset:51200
	ds_read_b128 v[172:175], v244 offset:52224
	ds_read_b128 v[176:179], v244 offset:53248
	ds_read_b128 v[180:183], v244 offset:54272
	ds_read_b128 v[184:187], v244 offset:55296
	ds_read_b128 v[188:191], v244 offset:56320
	global_load_lds_dwordx4 v[204:205], off
	s_add_i32 m0, s54, 0x2000
	s_add_u32 s6, s6, 0x40080
	v_lshl_add_u64 v[204:205], v[206:207], 0, s[20:21]
	s_addc_u32 s7, s7, 0
	s_add_i32 s54, s95, s8
	global_load_lds_dwordx4 v[204:205], off
	v_lshl_add_u64 v[204:205], s[6:7], 0, v[194:195]
	s_mov_b32 m0, s54
	s_nop 0
	global_load_lds_dwordx4 v[204:205], off
	v_lshl_add_u64 v[204:205], s[6:7], 0, v[198:199]
	s_add_i32 m0, s54, 0x2000
	s_nop 0
	global_load_lds_dwordx4 v[204:205], off
	v_lshl_add_u64 v[204:205], v[208:209], 0, s[20:21]
	s_mov_b32 m0, s58
	s_nop 0
	global_load_lds_dwordx4 v[204:205], off
	v_lshl_add_u64 v[204:205], v[210:211], 0, s[20:21]
	s_mov_b32 m0, s59
	s_nop 0
	global_load_lds_dwordx4 v[204:205], off
	s_waitcnt vmcnt(8)
	s_waitcnt lgkmcnt(0)
	s_barrier
	s_setprio 1
	s_waitcnt lgkmcnt(0)
	v_mfma_f32_16x16x32_bf16 v[60:63], v[128:131], v[160:163], v[60:63]
	v_mfma_f32_16x16x32_bf16 v[56:59], v[136:139], v[160:163], v[56:59]
	v_mfma_f32_16x16x32_bf16 v[52:55], v[128:131], v[168:171], v[52:55]
	v_mfma_f32_16x16x32_bf16 v[44:47], v[136:139], v[168:171], v[44:47]
	v_mfma_f32_16x16x32_bf16 v[36:39], v[128:131], v[176:179], v[36:39]
	v_mfma_f32_16x16x32_bf16 v[28:31], v[136:139], v[176:179], v[28:31]
	v_mfma_f32_16x16x32_bf16 v[20:23], v[128:131], v[184:187], v[20:23]
	v_mfma_f32_16x16x32_bf16 v[12:15], v[136:139], v[184:187], v[12:15]
	v_mfma_f32_16x16x32_bf16 v[60:63], v[132:135], v[164:167], v[60:63]
	v_mfma_f32_16x16x32_bf16 v[56:59], v[140:143], v[164:167], v[56:59]
	v_mfma_f32_16x16x32_bf16 v[52:55], v[132:135], v[172:175], v[52:55]
	v_mfma_f32_16x16x32_bf16 v[44:47], v[140:143], v[172:175], v[44:47]
	v_mfma_f32_16x16x32_bf16 v[36:39], v[132:135], v[180:183], v[36:39]
	v_mfma_f32_16x16x32_bf16 v[28:31], v[140:143], v[180:183], v[28:31]
	v_mfma_f32_16x16x32_bf16 v[20:23], v[132:135], v[188:191], v[20:23]
	v_mfma_f32_16x16x32_bf16 v[12:15], v[140:143], v[188:191], v[12:15]
	s_setprio 0
	s_setprio 1
	v_mfma_f32_16x16x32_bf16 v[48:51], v[144:147], v[160:163], v[48:51]
	v_mfma_f32_16x16x32_bf16 v[40:43], v[152:155], v[160:163], v[40:43]
	v_mfma_f32_16x16x32_bf16 v[32:35], v[144:147], v[168:171], v[32:35]
	v_mfma_f32_16x16x32_bf16 v[24:27], v[152:155], v[168:171], v[24:27]
	v_mfma_f32_16x16x32_bf16 v[16:19], v[144:147], v[176:179], v[16:19]
	v_mfma_f32_16x16x32_bf16 v[8:11], v[152:155], v[176:179], v[8:11]
	v_mfma_f32_16x16x32_bf16 v[4:7], v[144:147], v[184:187], v[4:7]
	v_mfma_f32_16x16x32_bf16 v[0:3], v[152:155], v[184:187], v[0:3]
	v_mfma_f32_16x16x32_bf16 v[48:51], v[148:151], v[164:167], v[48:51]
	v_mfma_f32_16x16x32_bf16 v[40:43], v[156:159], v[164:167], v[40:43]
	v_mfma_f32_16x16x32_bf16 v[32:35], v[148:151], v[172:175], v[32:35]
	v_mfma_f32_16x16x32_bf16 v[24:27], v[156:159], v[172:175], v[24:27]
	v_mfma_f32_16x16x32_bf16 v[16:19], v[148:151], v[180:183], v[16:19]
	v_mfma_f32_16x16x32_bf16 v[8:11], v[156:159], v[180:183], v[8:11]
	v_mfma_f32_16x16x32_bf16 v[4:7], v[148:151], v[188:191], v[4:7]
	v_mfma_f32_16x16x32_bf16 v[0:3], v[156:159], v[188:191], v[0:3]
	s_setprio 0
	s_barrier
	s_add_u32 s52, s52, 0x100
	s_addc_u32 s53, s53, 0
	s_add_u32 s91, s91, 0x100
	s_addc_u32 s92, s92, 0
	s_cmp_ge_u32 s93, s9
	s_mov_b32 s6, s93
	s_cbranch_scc0 .LBB0_1080
	s_branch .Lpeel_exit_out1

; #define PG8_STAGE(bufoff, gbase, voff) do { _Pragma("unroll") for (int _i = 0; _i < 2; ++_i) \
;         __builtin_amdgcn_global_load_lds((const unsigned*)((const char*)(gbase) + (voff)[_i]), (PG8_LAS unsigned*)(lds + (bufoff) + ldsw + _i * 8192), 16, 0, 0); } while (0)
; #define PG8_LDA(dst, b, h) do { _Pragma("unroll") for (int m = 0; m < 4; ++m) _Pragma("unroll") for (int k = 0; k < 2; ++k) dst[m][k] = *(const PG8_LAS bf16x8*)(lds + PG8_SA(b, h) + aoff + m * 2048 + k * 1024); } while (0)
; #define PG8_LDB(dst, b, h) do { _Pragma("unroll") for (int n = 0; n < 2; ++n) _Pragma("unroll") for (int k = 0; k < 2; ++k) dst[n][k] = *(const PG8_LAS bf16x8*)(lds + PG8_SB(b, h) + boff + n * 2048 + k * 1024); } while (0)
; #define PG8_WAIT_V(n) asm volatile("s_waitcnt vmcnt(" #n ")" ::: "memory")
; #define PG8_WAIT_L(n) asm volatile("s_waitcnt lgkmcnt(" #n ")" ::: "memory")
; #define PG8_BAR __builtin_amdgcn_s_barrier()
;     __host__ __device__ __forceinline__ bool next(int i, Unit& u) const { const long L = (long)i * G + c; if (L >= nwg) return false; map((int)L, u); return true; }
; template <class Epi, class Sched, bool ALIGN_EPI = false, bool SP2 = false>
; __device__ __forceinline__ void gemm_phase(PG8_LAS unsigned char* lds, const Gemm g, const Sched& S, const Epi& E) {
;     ...
;         const char* nA = has_next ? (const char*)g.A + (size_t)nxt.pm * tstepA + (size_t)(nxt.k0 >> 6) * kstepA + (nxt.qa > 0 ? hstepA : (size_t)0) : cA; const char* nB = has_next ? (const char*)g.Bt + (size_t)nxt.pn * tstepB + (size_t)nxt.k0 * 2 + (nxt.qb > 0 ? hstepB : (size_t)0) : cB;
;         const bool whole = cur.qa < 0;
;         const int nt = cur.nt;
;         for (int t = 0; t < nt; t += 2) {
;             const bool last = (t == nt - 2);
;             const char* a1 = cA + (size_t)(t + 1) * kstepA;
;             const char* a2 = last ? nA : cA + (size_t)(t + 2) * kstepA; const char* b2 = last ? nB : cB + (size_t)(t + 2) * kstep;
;             const char* a3 = a2 + kstepA; const char* b3 = b2 + kstep;
;             if (last && has_next) S.a_ready(nxt);
;             if constexpr (SP2) {
;             PG8_LDB(B0, 0, 0); PG8_LDB(B1, 0, 1); PG8_SCHED; PG8_LDA(At, 0, 0); PG8_STAGE(PG8_SA(1, 1), a1 + hstepA, voffA);
;             PG8_WAIT_V(8); PG8_WAIT_L(0); PG8_BAR; PG8_MMA(0, 0, At, B0); if (whole) PG8_MMA(0, 1, At, B1); PG8_BAR; PG8_SCHED;
.LBB0_1302:
	s_add_i32 s7, s36, s6
	s_ashr_i32 s6, s7, 31
	s_lshr_b32 s6, s6, 28
	s_add_i32 s36, s7, s6
	s_ashr_i32 s6, s36, 4
	s_lshl_b32 s37, s6, 2
	s_sub_i32 s6, 64, s37
	s_min_i32 s38, s6, 4
	s_abs_i32 s39, s38
	v_cvt_f32_u32_e32 v0, s39
	s_sub_i32 s43, 0, s39
	s_and_b32 s36, s36, -16
	s_sub_i32 s7, s7, s36
	v_rcp_iflag_f32_e32 v0, v0
	s_abs_i32 s36, s7
	s_max_i32 s40, s44, 0x100
	s_xor_b32 s42, s7, s38
	v_mul_f32_e32 v0, 0x4f7ffffe, v0
	v_cvt_u32_f32_e32 v0, v0
	s_add_i32 s41, s40, 0xffffff00
	s_ashr_i32 s42, s42, 31
	s_mov_b32 s6, 0
	v_readfirstlane_b32 s45, v0
	s_mul_i32 s43, s43, s45
	s_mul_hi_u32 s43, s45, s43
	s_add_i32 s45, s45, s43
	s_mul_hi_u32 s43, s36, s45
	s_mul_i32 s45, s43, s39
	s_sub_i32 s36, s36, s45
	s_add_i32 s45, s43, 1
	s_sub_i32 s54, s36, s39
	s_cmp_ge_u32 s36, s39
	s_cselect_b32 s43, s45, s43
	s_cselect_b32 s36, s54, s36
	s_add_i32 s45, s43, 1
	s_cmp_ge_u32 s36, s39
	s_cselect_b32 s36, s45, s43
	s_xor_b32 s36, s36, s42
	s_sub_i32 s42, s36, s42
	s_mul_i32 s36, s42, s38
	s_sub_i32 s7, s7, s36
	s_lshr_b32 s36, s41, 5
	s_add_i32 s7, s37, s7
	s_and_b32 s85, s40, 7
	s_add_i32 s38, s36, 64
	s_and_b64 s[36:37], s[26:27], exec
	s_cselect_b32 s36, s7, s38
	s_bfe_u32 s7, s40, 0x20003
	s_and_b64 s[38:39], s[26:27], exec
	s_cselect_b32 s38, s42, s7
	s_lshl_b32 s7, s85, 9
	s_and_b64 s[40:41], s[26:27], exec
	s_cselect_b32 s7, 0, s7
	s_ashr_i32 s37, s36, 31
	s_lshl_b64 s[40:41], s[36:37], 21
	s_add_u32 s37, s34, s40
	s_addc_u32 s39, s35, s41
	s_lshl_b32 s40, s7, 9
	s_add_u32 s40, s37, s40
	s_addc_u32 s41, s39, 0
	s_ashr_i32 s39, s38, 31
	s_lshl_b64 s[42:43], s[38:39], 21
	s_add_u32 s37, s12, s42
	s_addc_u32 s39, s13, s43
	s_lshl_b32 s7, s7, 1
	s_add_u32 s42, s37, s7
	s_addc_u32 s43, s39, 0
	s_cmpk_lt_i32 s44, 0x180
	s_cselect_b64 s[44:45], -1, 0
	s_and_b64 s[54:55], s[44:45], exec
	s_cselect_b32 s37, s41, s51
	s_cselect_b32 s39, s40, s50
	s_cselect_b32 s86, s43, s53
	s_cselect_b32 s87, s42, s52
	s_add_i32 s90, s9, -2
	s_add_u32 s91, s52, 0x100
	s_addc_u32 s92, s53, 0
	s_waitcnt lgkmcnt(0)
	ds_read_b128 v[128:131], v242
	ds_read_b128 v[132:135], v242 offset:1024
	ds_read_b128 v[136:139], v242 offset:2048
	ds_read_b128 v[140:143], v242 offset:3072
	ds_read_b128 v[144:147], v243
	ds_read_b128 v[148:151], v243 offset:1024
	ds_read_b128 v[152:155], v243 offset:2048
	ds_read_b128 v[156:159], v243 offset:3072
	s_add_i32 s93, s6, 2
	s_add_u32 s52, s50, 0x10000
	s_addc_u32 s53, s51, 0
	s_cmp_eq_u32 s90, s6
	s_cselect_b32 s56, s39, s52
	s_cselect_b32 s57, s37, s53
	s_cselect_b32 s54, s87, s91
	s_cselect_b32 s55, s86, s92
	s_add_u32 s6, s56, 0x8000
	s_addc_u32 s7, s57, 0
	v_lshl_add_u64 v[204:205], s[50:51], 0, v[200:201]
	s_add_i32 m0, s28, 0xc000
	ds_read_b128 v[160:163], v244
	ds_read_b128 v[164:167], v244 offset:1024
	ds_read_b128 v[168:171], v244 offset:2048
	ds_read_b128 v[172:175], v244 offset:3072
	ds_read_b128 v[176:179], v244 offset:4096
	ds_read_b128 v[180:183], v244 offset:5120
	ds_read_b128 v[184:187], v244 offset:6144
	ds_read_b128 v[188:191], v244 offset:7168
	global_load_lds_dwordx4 v[204:205], off
	v_lshl_add_u64 v[204:205], s[50:51], 0, v[202:203]
	s_add_i32 m0, s28, 0xe000
	s_nop 0
	global_load_lds_dwordx4 v[204:205], off
	s_waitcnt vmcnt(24)
	s_waitcnt lgkmcnt(0)
	s_barrier
	s_setprio 1
	s_waitcnt lgkmcnt(0)
	v_mfma_f32_16x16x32_bf16 v[124:127], v[128:131], v[160:163], 0
	v_mfma_f32_16x16x32_bf16 v[120:123], v[136:139], v[160:163], 0
	v_mfma_f32_16x16x32_bf16 v[116:119], v[128:131], v[168:171], 0
	v_mfma_f32_16x16x32_bf16 v[108:111], v[136:139], v[168:171], 0
	v_mfma_f32_16x16x32_bf16 v[100:103], v[128:131], v[176:179], 0
	v_mfma_f32_16x16x32_bf16 v[92:95], v[136:139], v[176:179], 0
	v_mfma_f32_16x16x32_bf16 v[84:87], v[128:131], v[184:187], 0
	v_mfma_f32_16x16x32_bf16 v[76:79], v[136:139], v[184:187], 0
	v_mfma_f32_16x16x32_bf16 v[124:127], v[132:135], v[164:167], v[124:127]
	v_mfma_f32_16x16x32_bf16 v[120:123], v[140:143], v[164:167], v[120:123]
	v_mfma_f32_16x16x32_bf16 v[116:119], v[132:135], v[172:175], v[116:119]
	v_mfma_f32_16x16x32_bf16 v[108:111], v[140:143], v[172:175], v[108:111]
	v_mfma_f32_16x16x32_bf16 v[100:103], v[132:135], v[180:183], v[100:103]
	v_mfma_f32_16x16x32_bf16 v[92:95], v[140:143], v[180:183], v[92:95]
	v_mfma_f32_16x16x32_bf16 v[84:87], v[132:135], v[188:191], v[84:87]
	v_mfma_f32_16x16x32_bf16 v[76:79], v[140:143], v[188:191], v[76:79]
	s_setprio 0
	s_setprio 1
	v_mfma_f32_16x16x32_bf16 v[112:115], v[144:147], v[160:163], 0
	v_mfma_f32_16x16x32_bf16 v[104:107], v[152:155], v[160:163], 0
	v_mfma_f32_16x16x32_bf16 v[96:99], v[144:147], v[168:171], 0
	v_mfma_f32_16x16x32_bf16 v[88:91], v[152:155], v[168:171], 0
	v_mfma_f32_16x16x32_bf16 v[80:83], v[144:147], v[176:179], 0
	v_mfma_f32_16x16x32_bf16 v[72:75], v[152:155], v[176:179], 0
	v_mfma_f32_16x16x32_bf16 v[68:71], v[144:147], v[184:187], 0
	v_mfma_f32_16x16x32_bf16 v[64:67], v[152:155], v[184:187], 0
	v_mfma_f32_16x16x32_bf16 v[112:115], v[148:151], v[164:167], v[112:115]
	v_mfma_f32_16x16x32_bf16 v[104:107], v[156:159], v[164:167], v[104:107]
	v_mfma_f32_16x16x32_bf16 v[96:99], v[148:151], v[172:175], v[96:99]
	v_mfma_f32_16x16x32_bf16 v[88:91], v[156:159], v[172:175], v[88:91]
	v_mfma_f32_16x16x32_bf16 v[80:83], v[148:151], v[180:183], v[80:83]
	v_mfma_f32_16x16x32_bf16 v[72:75], v[156:159], v[180:183], v[72:75]
	v_mfma_f32_16x16x32_bf16 v[68:71], v[148:151], v[188:191], v[68:71]
	v_mfma_f32_16x16x32_bf16 v[64:67], v[156:159], v[188:191], v[64:67]
	s_setprio 0
	s_barrier
; #define PG8_STAGE(bufoff, gbase, voff) do { _Pragma("unroll") for (int _i = 0; _i < 2; ++_i) \
;         __builtin_amdgcn_global_load_lds((const unsigned*)((const char*)(gbase) + (voff)[_i]), (PG8_LAS unsigned*)(lds + (bufoff) + ldsw + _i * 8192), 16, 0, 0); } while (0)
; #define PG8_LDA(dst, b, h) do { _Pragma("unroll") for (int m = 0; m < 4; ++m) _Pragma("unroll") for (int k = 0; k < 2; ++k) dst[m][k] = *(const PG8_LAS bf16x8*)(lds + PG8_SA(b, h) + aoff + m * 2048 + k * 1024); } while (0)
; #define PG8_LDB(dst, b, h) do { _Pragma("unroll") for (int n = 0; n < 2; ++n) _Pragma("unroll") for (int k = 0; k < 2; ++k) dst[n][k] = *(const PG8_LAS bf16x8*)(lds + PG8_SB(b, h) + boff + n * 2048 + k * 1024); } while (0)
; #define PG8_MMA(ai, bj, At, Bt) do { __builtin_amdgcn_s_setprio(1); _Pragma("unroll") for (int m = 0; m < 4; ++m) _Pragma("unroll") for (int n = 0; n < 2; ++n) _Pragma("unroll") for (int k = 0; k < 2; ++k) \
;         acc[ai][bj][m][n] = __builtin_amdgcn_mfma_f32_16x16x32_bf16(Bt[n][k], At[m][k], acc[ai][bj][m][n], 0, 0, 0); __builtin_amdgcn_s_setprio(0); } while (0)
; #define PG8_WAIT_V(n) asm volatile("s_waitcnt vmcnt(" #n ")" ::: "memory")
; #define PG8_WAIT_L(n) asm volatile("s_waitcnt lgkmcnt(" #n ")" ::: "memory")
; #define PG8_BAR __builtin_amdgcn_s_barrier()
; #define PG8_SCHED __builtin_amdgcn_sched_barrier(0)
; template <class Epi, class Sched, bool ALIGN_EPI = false, bool SP2 = false>
; __device__ __forceinline__ void gemm_phase(PG8_LAS unsigned char* lds, const Gemm g, const Sched& S, const Epi& E) {
;     ...
;             PG8_LDA(At, 0, 1); PG8_STAGE(PG8_SB(0, 0), b2, voffB); PG8_STAGE(PG8_SB(0, 1), b2 + hstepB, voffB); PG8_STAGE(PG8_SA(0, 0), a2, voffA);
;             PG8_WAIT_V(8); PG8_WAIT_L(0); PG8_BAR; if (whole) { PG8_MMA(1, 0, At, B0); PG8_MMA(1, 1, At, B1); } PG8_BAR; PG8_SCHED;
;             PG8_LDB(B0, 1, 0); PG8_LDB(B1, 1, 1); PG8_SCHED; PG8_LDA(At, 1, 0); PG8_STAGE(PG8_SA(0, 1), a2 + hstepA, voffA);
;             PG8_WAIT_V(8); PG8_WAIT_L(0); PG8_BAR; PG8_MMA(0, 0, At, B0); if (whole) PG8_MMA(0, 1, At, B1); PG8_BAR; PG8_SCHED;
;             PG8_LDA(At, 1, 1); PG8_STAGE(PG8_SB(1, 0), b3, voffB); PG8_STAGE(PG8_SB(1, 1), b3 + hstepB, voffB); PG8_STAGE(PG8_SA(1, 0), a3, voffA);
	s_add_i32 s50, s60, s8
	v_lshl_add_u64 v[204:205], s[54:55], 0, v[194:195]
	s_mov_b32 m0, s50
	ds_read_b128 v[160:163], v244 offset:16384
	ds_read_b128 v[164:167], v244 offset:17408
	ds_read_b128 v[168:171], v244 offset:18432
	ds_read_b128 v[172:175], v244 offset:19456
	ds_read_b128 v[176:179], v244 offset:20480
	ds_read_b128 v[180:183], v244 offset:21504
	ds_read_b128 v[184:187], v244 offset:22528
	ds_read_b128 v[188:191], v244 offset:23552
	global_load_lds_dwordx4 v[204:205], off
	s_add_i32 m0, s50, 0x2000
	s_add_u32 s50, s54, 0x100000
	v_lshl_add_u64 v[206:207], s[54:55], 0, v[198:199]
	s_addc_u32 s51, s55, 0
	s_add_i32 s94, s61, s8
	global_load_lds_dwordx4 v[206:207], off
	v_lshl_add_u64 v[208:209], s[50:51], 0, v[194:195]
	s_mov_b32 m0, s94
	s_nop 0
	global_load_lds_dwordx4 v[208:209], off
	v_lshl_add_u64 v[208:209], s[50:51], 0, v[198:199]
	s_add_i32 m0, s94, 0x2000
	s_nop 0
	global_load_lds_dwordx4 v[208:209], off
	v_lshl_add_u64 v[208:209], s[56:57], 0, v[192:193]
	s_mov_b32 m0, s28
	s_nop 0
	global_load_lds_dwordx4 v[208:209], off
	v_lshl_add_u64 v[208:209], s[56:57], 0, v[196:197]
	s_mov_b32 m0, s29
	s_nop 0
	global_load_lds_dwordx4 v[208:209], off
	s_waitcnt vmcnt(24)
	s_waitcnt lgkmcnt(0)
	s_barrier
	s_setprio 1
	s_waitcnt lgkmcnt(0)
	v_mfma_f32_16x16x32_bf16 v[60:63], v[128:131], v[160:163], 0
	v_mfma_f32_16x16x32_bf16 v[56:59], v[136:139], v[160:163], 0
	v_mfma_f32_16x16x32_bf16 v[52:55], v[128:131], v[168:171], 0
	v_mfma_f32_16x16x32_bf16 v[44:47], v[136:139], v[168:171], 0
	v_mfma_f32_16x16x32_bf16 v[36:39], v[128:131], v[176:179], 0
	v_mfma_f32_16x16x32_bf16 v[28:31], v[136:139], v[176:179], 0
	v_mfma_f32_16x16x32_bf16 v[20:23], v[128:131], v[184:187], 0
	v_mfma_f32_16x16x32_bf16 v[12:15], v[136:139], v[184:187], 0
	v_mfma_f32_16x16x32_bf16 v[60:63], v[132:135], v[164:167], v[60:63]
	v_mfma_f32_16x16x32_bf16 v[56:59], v[140:143], v[164:167], v[56:59]
	v_mfma_f32_16x16x32_bf16 v[52:55], v[132:135], v[172:175], v[52:55]
	v_mfma_f32_16x16x32_bf16 v[44:47], v[140:143], v[172:175], v[44:47]
	v_mfma_f32_16x16x32_bf16 v[36:39], v[132:135], v[180:183], v[36:39]
	v_mfma_f32_16x16x32_bf16 v[28:31], v[140:143], v[180:183], v[28:31]
	v_mfma_f32_16x16x32_bf16 v[20:23], v[132:135], v[188:191], v[20:23]
	v_mfma_f32_16x16x32_bf16 v[12:15], v[140:143], v[188:191], v[12:15]
	s_setprio 0
	s_setprio 1
	v_mfma_f32_16x16x32_bf16 v[48:51], v[144:147], v[160:163], 0
	v_mfma_f32_16x16x32_bf16 v[40:43], v[152:155], v[160:163], 0
	v_mfma_f32_16x16x32_bf16 v[32:35], v[144:147], v[168:171], 0
	v_mfma_f32_16x16x32_bf16 v[24:27], v[152:155], v[168:171], 0
	v_mfma_f32_16x16x32_bf16 v[16:19], v[144:147], v[176:179], 0
	v_mfma_f32_16x16x32_bf16 v[8:11], v[152:155], v[176:179], 0
	v_mfma_f32_16x16x32_bf16 v[4:7], v[144:147], v[184:187], 0
	v_mfma_f32_16x16x32_bf16 v[0:3], v[152:155], v[184:187], 0
	v_mfma_f32_16x16x32_bf16 v[48:51], v[148:151], v[164:167], v[48:51]
	v_mfma_f32_16x16x32_bf16 v[40:43], v[156:159], v[164:167], v[40:43]
	v_mfma_f32_16x16x32_bf16 v[32:35], v[148:151], v[172:175], v[32:35]
	v_mfma_f32_16x16x32_bf16 v[24:27], v[156:159], v[172:175], v[24:27]
	v_mfma_f32_16x16x32_bf16 v[16:19], v[148:151], v[180:183], v[16:19]
	v_mfma_f32_16x16x32_bf16 v[8:11], v[156:159], v[180:183], v[8:11]
	v_mfma_f32_16x16x32_bf16 v[4:7], v[148:151], v[188:191], v[4:7]
	v_mfma_f32_16x16x32_bf16 v[0:3], v[156:159], v[188:191], v[0:3]
	s_setprio 0
	s_barrier
	s_add_i32 s94, 0, 0x18000
	s_add_i32 s95, 0, 0x1c000
	v_add_u32_e32 v140, s94, v240
	v_add_u32_e32 v156, s95, v240
	ds_read_b128 v[128:131], v140
	ds_read_b128 v[132:135], v140 offset:1024
	ds_read_b128 v[136:139], v140 offset:2048
	ds_read_b128 v[140:143], v140 offset:3072
	ds_read_b128 v[144:147], v156
	ds_read_b128 v[148:151], v156 offset:1024
	ds_read_b128 v[152:155], v156 offset:2048
	ds_read_b128 v[156:159], v156 offset:3072
	s_add_u32 s50, s56, 0x2000
	s_addc_u32 s51, s57, 0
	s_mov_b32 m0, s47
	v_lshl_add_u64 v[208:209], s[50:51], 0, v[192:193]
	ds_read_b128 v[160:163], v244 offset:32768
	ds_read_b128 v[164:167], v244 offset:33792
	ds_read_b128 v[168:171], v244 offset:34816
	ds_read_b128 v[172:175], v244 offset:35840
	ds_read_b128 v[176:179], v244 offset:36864
	ds_read_b128 v[180:183], v244 offset:37888
	ds_read_b128 v[184:187], v244 offset:38912
	ds_read_b128 v[188:191], v244 offset:39936
	global_load_lds_dwordx4 v[208:209], off
	v_lshl_add_u64 v[208:209], s[50:51], 0, v[196:197]
	s_mov_b32 m0, s49
	s_nop 0
	global_load_lds_dwordx4 v[208:209], off
	s_waitcnt vmcnt(8)
	s_waitcnt lgkmcnt(0)
	s_barrier
; #define PG8_STAGE(bufoff, gbase, voff) do { _Pragma("unroll") for (int _i = 0; _i < 2; ++_i) \
;         __builtin_amdgcn_global_load_lds((const unsigned*)((const char*)(gbase) + (voff)[_i]), (PG8_LAS unsigned*)(lds + (bufoff) + ldsw + _i * 8192), 16, 0, 0); } while (0)
; #define PG8_LDA(dst, b, h) do { _Pragma("unroll") for (int m = 0; m < 4; ++m) _Pragma("unroll") for (int k = 0; k < 2; ++k) dst[m][k] = *(const PG8_LAS bf16x8*)(lds + PG8_SA(b, h) + aoff + m * 2048 + k * 1024); } while (0)
; #define PG8_MMA(ai, bj, At, Bt) do { __builtin_amdgcn_s_setprio(1); _Pragma("unroll") for (int m = 0; m < 4; ++m) _Pragma("unroll") for (int n = 0; n < 2; ++n) _Pragma("unroll") for (int k = 0; k < 2; ++k) \
;         acc[ai][bj][m][n] = __builtin_amdgcn_mfma_f32_16x16x32_bf16(Bt[n][k], At[m][k], acc[ai][bj][m][n], 0, 0, 0); __builtin_amdgcn_s_setprio(0); } while (0)
; #define PG8_WAIT_V(n) asm volatile("s_waitcnt vmcnt(" #n ")" ::: "memory")
; #define PG8_WAIT_L(n) asm volatile("s_waitcnt lgkmcnt(" #n ")" ::: "memory")
; #define PG8_BAR __builtin_amdgcn_s_barrier()
; #define PG8_SCHED __builtin_amdgcn_sched_barrier(0)
; template <class Epi, class Sched, bool ALIGN_EPI = false, bool SP2 = false>
; __device__ __forceinline__ void gemm_phase(PG8_LAS unsigned char* lds, const Gemm g, const Sched& S, const Epi& E) {
;     ...
;             PG8_WAIT_V(8); PG8_WAIT_L(0); PG8_BAR; PG8_MMA(0, 0, At, B0); if (whole) PG8_MMA(0, 1, At, B1); PG8_BAR; PG8_SCHED;
;             PG8_LDA(At, 1, 1); PG8_STAGE(PG8_SB(1, 0), b3, voffB); PG8_STAGE(PG8_SB(1, 1), b3 + hstepB, voffB); PG8_STAGE(PG8_SA(1, 0), a3, voffA);
;             PG8_WAIT_V(8); PG8_WAIT_L(0); PG8_BAR; if (whole) { PG8_MMA(1, 0, At, B0); PG8_MMA(1, 1, At, B1); } PG8_BAR; PG8_SCHED;
	s_setprio 1
	s_waitcnt lgkmcnt(0)
	v_mfma_f32_16x16x32_bf16 v[124:127], v[128:131], v[160:163], v[124:127]
	v_mfma_f32_16x16x32_bf16 v[120:123], v[136:139], v[160:163], v[120:123]
	v_mfma_f32_16x16x32_bf16 v[116:119], v[128:131], v[168:171], v[116:119]
	v_mfma_f32_16x16x32_bf16 v[108:111], v[136:139], v[168:171], v[108:111]
	v_mfma_f32_16x16x32_bf16 v[100:103], v[128:131], v[176:179], v[100:103]
	v_mfma_f32_16x16x32_bf16 v[92:95], v[136:139], v[176:179], v[92:95]
	v_mfma_f32_16x16x32_bf16 v[84:87], v[128:131], v[184:187], v[84:87]
	v_mfma_f32_16x16x32_bf16 v[76:79], v[136:139], v[184:187], v[76:79]
	v_mfma_f32_16x16x32_bf16 v[124:127], v[132:135], v[164:167], v[124:127]
	v_mfma_f32_16x16x32_bf16 v[120:123], v[140:143], v[164:167], v[120:123]
	v_mfma_f32_16x16x32_bf16 v[116:119], v[132:135], v[172:175], v[116:119]
	v_mfma_f32_16x16x32_bf16 v[108:111], v[140:143], v[172:175], v[108:111]
	v_mfma_f32_16x16x32_bf16 v[100:103], v[132:135], v[180:183], v[100:103]
	v_mfma_f32_16x16x32_bf16 v[92:95], v[140:143], v[180:183], v[92:95]
	v_mfma_f32_16x16x32_bf16 v[84:87], v[132:135], v[188:191], v[84:87]
	v_mfma_f32_16x16x32_bf16 v[76:79], v[140:143], v[188:191], v[76:79]
	s_setprio 0
	s_setprio 1
	v_mfma_f32_16x16x32_bf16 v[112:115], v[144:147], v[160:163], v[112:115]
	v_mfma_f32_16x16x32_bf16 v[104:107], v[152:155], v[160:163], v[104:107]
	v_mfma_f32_16x16x32_bf16 v[96:99], v[144:147], v[168:171], v[96:99]
	v_mfma_f32_16x16x32_bf16 v[88:91], v[152:155], v[168:171], v[88:91]
	v_mfma_f32_16x16x32_bf16 v[80:83], v[144:147], v[176:179], v[80:83]
	v_mfma_f32_16x16x32_bf16 v[72:75], v[152:155], v[176:179], v[72:75]
	v_mfma_f32_16x16x32_bf16 v[68:71], v[144:147], v[184:187], v[68:71]
	v_mfma_f32_16x16x32_bf16 v[64:67], v[152:155], v[184:187], v[64:67]
	v_mfma_f32_16x16x32_bf16 v[112:115], v[148:151], v[164:167], v[112:115]
	v_mfma_f32_16x16x32_bf16 v[104:107], v[156:159], v[164:167], v[104:107]
	v_mfma_f32_16x16x32_bf16 v[96:99], v[148:151], v[172:175], v[96:99]
	v_mfma_f32_16x16x32_bf16 v[88:91], v[156:159], v[172:175], v[88:91]
	v_mfma_f32_16x16x32_bf16 v[80:83], v[148:151], v[180:183], v[80:83]
	v_mfma_f32_16x16x32_bf16 v[72:75], v[156:159], v[180:183], v[72:75]
	v_mfma_f32_16x16x32_bf16 v[68:71], v[148:151], v[188:191], v[68:71]
	v_mfma_f32_16x16x32_bf16 v[64:67], v[156:159], v[188:191], v[64:67]
	s_setprio 0
	s_barrier
	s_add_i32 s50, s94, s8
	v_lshl_add_u64 v[204:205], v[204:205], 0, s[20:21]
	s_mov_b32 m0, s50
	ds_read_b128 v[160:163], v244 offset:49152
	ds_read_b128 v[164:167], v244 offset:50176
	ds_read_b128 v[168:171], v244 offset:51200
	ds_read_b128 v[172:175], v244 offset:52224
	ds_read_b128 v[176:179], v244 offset:53248
	ds_read_b128 v[180:183], v244 offset:54272
	ds_read_b128 v[184:187], v244 offset:55296
	ds_read_b128 v[188:191], v244 offset:56320
	global_load_lds_dwordx4 v[204:205], off
	s_add_i32 m0, s50, 0x2000
	s_add_u32 s50, s54, 0x100080
	v_lshl_add_u64 v[204:205], v[206:207], 0, s[20:21]
	s_addc_u32 s51, s55, 0
	s_add_i32 s54, s95, s8
	global_load_lds_dwordx4 v[204:205], off
	v_lshl_add_u64 v[204:205], s[50:51], 0, v[194:195]
	s_mov_b32 m0, s54
	s_nop 0
	global_load_lds_dwordx4 v[204:205], off
	v_lshl_add_u64 v[204:205], s[50:51], 0, v[198:199]
	s_add_i32 m0, s54, 0x2000
	s_nop 0
	global_load_lds_dwordx4 v[204:205], off
	v_lshl_add_u64 v[204:205], s[6:7], 0, v[192:193]
	s_mov_b32 m0, s58
	s_nop 0
	global_load_lds_dwordx4 v[204:205], off
	v_lshl_add_u64 v[204:205], s[6:7], 0, v[196:197]
	s_mov_b32 m0, s59
	s_nop 0
	global_load_lds_dwordx4 v[204:205], off
	s_waitcnt vmcnt(8)
	s_waitcnt lgkmcnt(0)
	s_barrier
	s_setprio 1
	s_waitcnt lgkmcnt(0)
	v_mfma_f32_16x16x32_bf16 v[60:63], v[128:131], v[160:163], v[60:63]
	v_mfma_f32_16x16x32_bf16 v[56:59], v[136:139], v[160:163], v[56:59]
	v_mfma_f32_16x16x32_bf16 v[52:55], v[128:131], v[168:171], v[52:55]
	v_mfma_f32_16x16x32_bf16 v[44:47], v[136:139], v[168:171], v[44:47]
	v_mfma_f32_16x16x32_bf16 v[36:39], v[128:131], v[176:179], v[36:39]
	v_mfma_f32_16x16x32_bf16 v[28:31], v[136:139], v[176:179], v[28:31]
	v_mfma_f32_16x16x32_bf16 v[20:23], v[128:131], v[184:187], v[20:23]
	v_mfma_f32_16x16x32_bf16 v[12:15], v[136:139], v[184:187], v[12:15]
	v_mfma_f32_16x16x32_bf16 v[60:63], v[132:135], v[164:167], v[60:63]
	v_mfma_f32_16x16x32_bf16 v[56:59], v[140:143], v[164:167], v[56:59]
	v_mfma_f32_16x16x32_bf16 v[52:55], v[132:135], v[172:175], v[52:55]
	v_mfma_f32_16x16x32_bf16 v[44:47], v[140:143], v[172:175], v[44:47]
	v_mfma_f32_16x16x32_bf16 v[36:39], v[132:135], v[180:183], v[36:39]
	v_mfma_f32_16x16x32_bf16 v[28:31], v[140:143], v[180:183], v[28:31]
	v_mfma_f32_16x16x32_bf16 v[20:23], v[132:135], v[188:191], v[20:23]
	v_mfma_f32_16x16x32_bf16 v[12:15], v[140:143], v[188:191], v[12:15]
	s_setprio 0
	s_setprio 1
	v_mfma_f32_16x16x32_bf16 v[48:51], v[144:147], v[160:163], v[48:51]
	v_mfma_f32_16x16x32_bf16 v[40:43], v[152:155], v[160:163], v[40:43]
	v_mfma_f32_16x16x32_bf16 v[32:35], v[144:147], v[168:171], v[32:35]
	v_mfma_f32_16x16x32_bf16 v[24:27], v[152:155], v[168:171], v[24:27]
	v_mfma_f32_16x16x32_bf16 v[16:19], v[144:147], v[176:179], v[16:19]
	v_mfma_f32_16x16x32_bf16 v[8:11], v[152:155], v[176:179], v[8:11]
	v_mfma_f32_16x16x32_bf16 v[4:7], v[144:147], v[184:187], v[4:7]
	v_mfma_f32_16x16x32_bf16 v[0:3], v[152:155], v[184:187], v[0:3]
	v_mfma_f32_16x16x32_bf16 v[48:51], v[148:151], v[164:167], v[48:51]
	v_mfma_f32_16x16x32_bf16 v[40:43], v[156:159], v[164:167], v[40:43]
	v_mfma_f32_16x16x32_bf16 v[32:35], v[148:151], v[172:175], v[32:35]
	v_mfma_f32_16x16x32_bf16 v[24:27], v[156:159], v[172:175], v[24:27]
	v_mfma_f32_16x16x32_bf16 v[16:19], v[148:151], v[180:183], v[16:19]
	v_mfma_f32_16x16x32_bf16 v[8:11], v[156:159], v[180:183], v[8:11]
	v_mfma_f32_16x16x32_bf16 v[4:7], v[148:151], v[188:191], v[4:7]
	v_mfma_f32_16x16x32_bf16 v[0:3], v[156:159], v[188:191], v[0:3]
	s_setprio 0
	s_barrier
	s_add_u32 s91, s91, 0x100
	s_addc_u32 s92, s92, 0
	s_cmp_ge_u32 s93, s9
	s_mov_b64 s[50:51], s[52:53]
	s_mov_b32 s6, s93
	s_cbranch_scc0 .LBB0_1303
	s_branch .Lpeel_exit_down1
